# nontemporal hint on the bf16 weight stores of the transpose items (written once, first re-read much later), on top of the four-slot overlap
# speedup vs baseline: 1.0013x; 1.0013x over previous
; __device__ __forceinline__ void phase_prologue(const P& p, unsigned char* ws, LAS unsigned char* lds, int wg, int nwg) {
;     ...
;     for (int it = gw; it < DEPTH * I_LAYER; it += NGW) {
;         const int l = it / I_LAYER; int r = it % I_LAYER;
;         if (r < I_IN) { const int nb = r % (NZ / 32), kb = r / (NZ / 32), n0 = nb * 32; bf16_t* WT = (bf16_t*)(ws + WS_WIN) + (size_t)l * NZ * D; const float* Win = p.w_in + (size_t)l * D * NIN; const float* kg = p.n_pre_mix + l * D;
;             if (n0 >= 7168 && n0 < 7680) fold_item(Win, p.wgg + (size_t)l * GR * GKW, kg, WT, kb * 64, n0 - 7168, n0, scr, lane);
;             else { const int ns = n0 < 7168 ? n0 : n0 - 496; const float sc = (n0 >= 4096 && n0 < 4608) ? 0.08838834764831845f : 1.f; transpose_item(Win, NIN, kg, sc, WT, D, kb * 64, ns, n0, scr, lane); }
;             continue; } r -= I_IN;
;         if (r < I_UH) { transpose_item(p.w_hup + (size_t)l * HW * D, D, nullptr, 1.f, (bf16_t*)(ws + WS_WUH) + (size_t)l * D * HW, HW, (r / (D / 32)) * 64, (r % (D / 32)) * 32, (r % (D / 32)) * 32, scr, lane); continue; } r -= I_UH;
;         if (r < I_UG) { transpose_item(p.w_gup + (size_t)l * GVW * D, D, nullptr, 1.f, (bf16_t*)(ws + WS_WUG) + (size_t)l * D * GVW, GVW, (r / (D / 32)) * 64, (r % (D / 32)) * 32, (r % (D / 32)) * 32, scr, lane); continue; } r -= I_UG;
;         if (r < I_OUT) { transpose_item(p.w_out + (size_t)l * D * D, D, nullptr, 1.f, (bf16_t*)(ws + WS_WOUT) + (size_t)l * D * D, D, (r / (D / 32)) * 64, (r % (D / 32)) * 32, (r % (D / 32)) * 32, scr, lane); continue; } r -= I_OUT;
;         if (r < I_F1) { transpose_item(p.w_ff1 + (size_t)l * D * DFF, DFF, p.n_pre_ffn + l * D, 1.f, (bf16_t*)(ws + WS_WFF1) + (size_t)l * DFF * D, D, (r / (DFF / 32)) * 64, (r % (DFF / 32)) * 32, (r % (DFF / 32)) * 32, scr, lane); continue; } r -= I_F1;
;         if (r < I_F2) { transpose_item(p.w_ff2 + (size_t)l * DFF * D, D, nullptr, 1.f, (bf16_t*)(ws + WS_WFF2) + (size_t)l * D * DFF, DFF, (r / (D / 32)) * 64, (r % (D / 32)) * 32, (r % (D / 32)) * 32, scr, lane); continue; } r -= I_F2;
;         if (r < I_PL) { transpose_item(p.w_ple + (size_t)l * PLE * D, D, nullptr, 1.f, (bf16_t*)(ws + WS_WPLE) + (size_t)l * D * PLE, PLE, (r / (D / 32)) * 64, (r % (D / 32)) * 32, (r % (D / 32)) * 32, scr, lane); continue; } r -= I_PL;
.LBB0_12:
	s_mov_b32 s33, 0xf2b9d649
	v_mul_hi_i32 v12, v68, s33
	v_add_u32_e32 v12, v12, v68
	v_lshrrev_b32_e32 v16, 31, v12
	v_ashrrev_i32_e32 v12, 15, v12
	v_add_u32_e32 v20, v12, v16
	v_mul_i32_i24_e32 v12, 0x8700, v20
	v_sub_u32_e32 v12, v68, v12
	s_movk_i32 s33, 0x2dff
	v_cmp_lt_i32_e32 vcc, s33, v12
	s_and_saveexec_b64 s[44:45], vcc
	s_xor_b64 s[80:81], exec, s[44:45]
	s_cbranch_execz .LBB0_40
	s_movk_i32 s33, 0x31ff
	v_cmp_lt_u32_e32 vcc, s33, v12
	s_and_saveexec_b64 s[44:45], vcc
	s_xor_b64 s[82:83], exec, s[44:45]
	s_cbranch_execz .LBB0_37
	s_movk_i32 s33, 0x35ff
	v_cmp_lt_u32_e32 vcc, s33, v12
	s_and_saveexec_b64 s[44:45], vcc
	s_xor_b64 s[84:85], exec, s[44:45]
	s_cbranch_execz .LBB0_34
	s_movk_i32 s33, 0x3dff
	v_cmp_lt_u32_e32 vcc, s33, v12
	s_and_saveexec_b64 s[44:45], vcc
	s_xor_b64 s[86:87], exec, s[44:45]
	s_cbranch_execz .LBB0_31
	s_movk_i32 s33, 0x5dff
	v_cmp_lt_u32_e32 vcc, s33, v12
	v_ashrrev_i32_e32 v21, 31, v20
	s_and_saveexec_b64 s[44:45], vcc
	s_xor_b64 s[88:89], exec, s[44:45]
	s_cbranch_execz .LBB0_26
	s_movk_i32 s33, 0x7dff
	v_cmp_lt_u32_e32 vcc, s33, v12
	s_and_saveexec_b64 s[44:45], vcc
	s_xor_b64 s[90:91], exec, s[44:45]
	s_cbranch_execz .LBB0_23
	s_movk_i32 s33, 0x7eff
	v_cmp_lt_u32_e32 vcc, s33, v12
	s_and_saveexec_b64 s[44:45], vcc
	s_xor_b64 s[44:45], exec, s[44:45]
	s_cbranch_execz .LBB0_20
	v_lshlrev_b64 v[16:17], 24, v[20:21]
	v_lshl_add_u64 v[18:19], s[52:53], 0, v[16:17]
	v_and_b32_e32 v16, 0x7fffffc0, v12
	v_lshlrev_b32_e32 v12, 5, v12
	v_and_b32_e32 v40, 0x7e0, v12
	v_add_u32_e32 v16, 0xffff8100, v16
	v_lshlrev_b32_e32 v12, 2, v40
	v_or_b32_e32 v22, v16, v8
	v_lshl_add_u64 v[18:19], v[18:19], 0, v[12:13]
	v_lshlrev_b32_e32 v12, 2, v10
	v_lshl_add_u64 v[18:19], v[18:19], 0, v[12:13]
	v_or_b32_e32 v12, 2, v22
	v_lshlrev_b64 v[26:27], 13, v[12:13]
	v_or_b32_e32 v12, 4, v22
	v_lshlrev_b64 v[28:29], 13, v[12:13]
	v_or_b32_e32 v12, 6, v22
	v_lshlrev_b64 v[30:31], 13, v[12:13]
	v_or_b32_e32 v12, 8, v22
	v_lshlrev_b64 v[32:33], 13, v[12:13]
	v_or_b32_e32 v12, 10, v22
	v_mov_b32_e32 v23, v13
	v_lshlrev_b64 v[34:35], 13, v[12:13]
	v_or_b32_e32 v12, 12, v22
	v_lshlrev_b64 v[24:25], 13, v[22:23]
	v_lshlrev_b64 v[36:37], 13, v[12:13]
	v_or_b32_e32 v12, 14, v22
	v_lshl_add_u64 v[24:25], v[18:19], 0, v[24:25]
	v_lshlrev_b64 v[38:39], 13, v[12:13]
	v_or_b32_e32 v12, 16, v22
	v_lshl_add_u64 v[26:27], v[18:19], 0, v[26:27]
	v_lshl_add_u64 v[28:29], v[18:19], 0, v[28:29]
	v_lshl_add_u64 v[30:31], v[18:19], 0, v[30:31]
	v_lshl_add_u64 v[32:33], v[18:19], 0, v[32:33]
	v_lshl_add_u64 v[34:35], v[18:19], 0, v[34:35]
	v_lshl_add_u64 v[36:37], v[18:19], 0, v[36:37]
	v_lshl_add_u64 v[38:39], v[18:19], 0, v[38:39]
	global_load_dword v17, v[24:25], off
	global_load_dword v41, v[26:27], off
	global_load_dword v42, v[28:29], off
	global_load_dword v43, v[30:31], off
	global_load_dword v44, v[32:33], off
	global_load_dword v45, v[34:35], off
	global_load_dword v46, v[36:37], off
	global_load_dword v47, v[38:39], off
	v_lshlrev_b64 v[24:25], 13, v[12:13]
	v_or_b32_e32 v12, 18, v22
	v_lshlrev_b64 v[26:27], 13, v[12:13]
	v_or_b32_e32 v12, 20, v22
	v_lshlrev_b64 v[28:29], 13, v[12:13]
	v_or_b32_e32 v12, 22, v22
	v_lshlrev_b64 v[30:31], 13, v[12:13]
	v_or_b32_e32 v12, 24, v22
	v_lshlrev_b64 v[32:33], 13, v[12:13]
	v_or_b32_e32 v12, 26, v22
	v_lshlrev_b64 v[34:35], 13, v[12:13]
	v_or_b32_e32 v12, 28, v22
	v_lshlrev_b64 v[36:37], 13, v[12:13]
	v_or_b32_e32 v12, 30, v22
	v_lshl_add_u64 v[24:25], v[18:19], 0, v[24:25]
	v_lshlrev_b64 v[38:39], 13, v[12:13]
	v_or_b32_e32 v12, 32, v22
	v_lshl_add_u64 v[26:27], v[18:19], 0, v[26:27]
	v_lshl_add_u64 v[28:29], v[18:19], 0, v[28:29]
	v_lshl_add_u64 v[30:31], v[18:19], 0, v[30:31]
	v_lshl_add_u64 v[32:33], v[18:19], 0, v[32:33]
	v_lshl_add_u64 v[34:35], v[18:19], 0, v[34:35]
	v_lshl_add_u64 v[36:37], v[18:19], 0, v[36:37]
	v_lshl_add_u64 v[38:39], v[18:19], 0, v[38:39]
	global_load_dword v48, v[24:25], off
	global_load_dword v49, v[26:27], off
	global_load_dword v50, v[28:29], off
	global_load_dword v51, v[30:31], off
	global_load_dword v52, v[32:33], off
	global_load_dword v53, v[34:35], off
	global_load_dword v54, v[36:37], off
	global_load_dword v55, v[38:39], off
	v_lshlrev_b64 v[24:25], 13, v[12:13]
	v_or_b32_e32 v12, 34, v22
	v_lshlrev_b64 v[26:27], 13, v[12:13]
	v_or_b32_e32 v12, 36, v22
	v_lshlrev_b64 v[28:29], 13, v[12:13]
	v_or_b32_e32 v12, 38, v22
	v_lshlrev_b64 v[30:31], 13, v[12:13]
	v_or_b32_e32 v12, 40, v22
	v_lshlrev_b64 v[32:33], 13, v[12:13]
	v_or_b32_e32 v12, 42, v22
	v_lshlrev_b64 v[34:35], 13, v[12:13]
	v_or_b32_e32 v12, 44, v22
	v_lshlrev_b64 v[36:37], 13, v[12:13]
	v_or_b32_e32 v12, 46, v22
	v_lshlrev_b64 v[38:39], 13, v[12:13]
	v_lshl_add_u64 v[24:25], v[18:19], 0, v[24:25]
	v_lshl_add_u64 v[38:39], v[18:19], 0, v[38:39]
	v_or_b32_e32 v12, 48, v22
	v_lshl_add_u64 v[26:27], v[18:19], 0, v[26:27]
	v_lshl_add_u64 v[28:29], v[18:19], 0, v[28:29]
	v_lshl_add_u64 v[30:31], v[18:19], 0, v[30:31]
	v_lshl_add_u64 v[32:33], v[18:19], 0, v[32:33]
	v_lshl_add_u64 v[34:35], v[18:19], 0, v[34:35]
	v_lshl_add_u64 v[36:37], v[18:19], 0, v[36:37]
	global_load_dword v69, v[24:25], off
	global_load_dword v70, v[26:27], off
	global_load_dword v71, v[28:29], off
	global_load_dword v72, v[30:31], off
	global_load_dword v73, v[32:33], off
	global_load_dword v74, v[34:35], off
	global_load_dword v75, v[36:37], off
	s_nop 0
	global_load_dword v38, v[38:39], off
	v_lshlrev_b64 v[24:25], 13, v[12:13]
	v_or_b32_e32 v12, 50, v22
	v_lshlrev_b64 v[26:27], 13, v[12:13]
	v_or_b32_e32 v12, 52, v22
	v_lshlrev_b64 v[28:29], 13, v[12:13]
	v_or_b32_e32 v12, 54, v22
	v_lshlrev_b64 v[30:31], 13, v[12:13]
	v_or_b32_e32 v12, 56, v22
	v_lshlrev_b64 v[32:33], 13, v[12:13]
	v_or_b32_e32 v12, 58, v22
	v_lshlrev_b64 v[34:35], 13, v[12:13]
	v_or_b32_e32 v12, 60, v22
	v_lshlrev_b64 v[36:37], 13, v[12:13]
	v_or_b32_e32 v12, 62, v22
	v_lshl_add_u64 v[24:25], v[18:19], 0, v[24:25]
	v_lshl_add_u64 v[26:27], v[18:19], 0, v[26:27]
	v_lshl_add_u64 v[28:29], v[18:19], 0, v[28:29]
	v_lshlrev_b64 v[22:23], 13, v[12:13]
	v_lshl_add_u64 v[30:31], v[18:19], 0, v[30:31]
	v_lshl_add_u64 v[32:33], v[18:19], 0, v[32:33]
	v_lshl_add_u64 v[34:35], v[18:19], 0, v[34:35]
	v_lshl_add_u64 v[36:37], v[18:19], 0, v[36:37]
	v_lshl_add_u64 v[18:19], v[18:19], 0, v[22:23]
	global_load_dword v12, v[24:25], off
	global_load_dword v22, v[26:27], off
	global_load_dword v23, v[28:29], off
	s_nop 0
	global_load_dword v24, v[30:31], off
	global_load_dword v25, v[32:33], off
	global_load_dword v26, v[34:35], off
	global_load_dword v27, v[36:37], off
	global_load_dword v28, v[18:19], off
	s_waitcnt vmcnt(30)
; #define LAS __attribute__((address_space(3)))
; __device__ __forceinline__ unsigned pk2(float lo, float hi) { return pg8::cvt_pk_bf16(lo, hi); }
; __device__ __forceinline__ void transpose_item(const float* W, int ldw, const float* kgain, float scale, bf16_t* WT, int ldt, int k0, int n_src0, int n_dst0, LAS float* scr, int lane) {
;     ...
;     for (int i = 0; i < 32; ++i) scr[(2 * i + (lane >> 5)) * 33 + (lane & 31)] = wv[i];
;     asm volatile("s_waitcnt lgkmcnt(0)" ::: "memory");
;     const int c = lane & 7;
; #pragma unroll
;     for (int j = 0; j < 4; ++j) { const int n = (lane >> 3) + 8 * j; const LAS float* s = scr + (8 * c) * 33 + n;
;         u32x4 o; o.x = pk2(s[0 * 33], s[1 * 33]); o.y = pk2(s[2 * 33], s[3 * 33]); o.z = pk2(s[4 * 33], s[5 * 33]); o.w = pk2(s[6 * 33], s[7 * 33]);
;         *(u32x4*)(WT + (size_t)(n_dst0 + n) * ldt + k0 + 8 * c) = o; }
;     asm volatile("s_waitcnt lgkmcnt(0)" ::: "memory");
; __device__ __forceinline__ void phase_prologue(const P& p, unsigned char* ws, LAS unsigned char* lds, int wg, int nwg) {
;     ...
;         if (r < I_PL) { transpose_item(p.w_ple + (size_t)l * PLE * D, D, nullptr, 1.f, (bf16_t*)(ws + WS_WPLE) + (size_t)l * D * PLE, PLE, (r / (D / 32)) * 64, (r % (D / 32)) * 32, (r % (D / 32)) * 32, scr, lane); continue; } r -= I_PL;
	ds_write2_b32 v5, v17, v41 offset1:66
	s_waitcnt vmcnt(28)
	ds_write2_b32 v5, v42, v43 offset0:132 offset1:198
	v_add_u32_e32 v17, 0x400, v5
	s_waitcnt vmcnt(26)
	ds_write2_b32 v17, v44, v45 offset0:8 offset1:74
	s_waitcnt vmcnt(24)
	ds_write2_b32 v17, v46, v47 offset0:140 offset1:206
	v_add_u32_e32 v17, 0x800, v5
	s_waitcnt vmcnt(22)
	ds_write2_b32 v17, v48, v49 offset0:16 offset1:82
	s_waitcnt vmcnt(20)
	ds_write2_b32 v17, v50, v51 offset0:148 offset1:214
	v_add_u32_e32 v17, 0xc00, v5
	s_waitcnt vmcnt(18)
	ds_write2_b32 v17, v52, v53 offset0:24 offset1:90
	s_waitcnt vmcnt(16)
	ds_write2_b32 v17, v54, v55 offset0:156 offset1:222
	v_add_u32_e32 v17, 0x1000, v5
	s_waitcnt vmcnt(14)
	ds_write2_b32 v17, v69, v70 offset0:32 offset1:98
	s_waitcnt vmcnt(12)
	ds_write2_b32 v17, v71, v72 offset0:164 offset1:230
	v_add_u32_e32 v17, 0x1400, v5
	s_waitcnt vmcnt(10)
	ds_write2_b32 v17, v73, v74 offset0:40 offset1:106
	s_waitcnt vmcnt(8)
	ds_write2_b32 v17, v75, v38 offset0:172 offset1:238
	v_add_u32_e32 v17, 0x1800, v5
	s_waitcnt vmcnt(6)
	ds_write2_b32 v17, v12, v22 offset0:48 offset1:114
	s_waitcnt vmcnt(4)
	ds_write2_b32 v17, v23, v24 offset0:180 offset1:246
	v_add_u32_e32 v12, 0x1c00, v5
	s_waitcnt vmcnt(2)
	ds_write2_b32 v12, v25, v26 offset0:56 offset1:122
	s_waitcnt vmcnt(0)
	ds_write2_b32 v12, v27, v28 offset0:188 offset1:254
	s_waitcnt lgkmcnt(0)
	v_lshlrev_b64 v[18:19], 23, v[20:21]
	ds_read2_b32 v[20:21], v11 offset0:33 offset1:41
	ds_read2_b32 v[22:23], v11 offset1:8
	ds_read2_b32 v[24:25], v11 offset0:66 offset1:74
	ds_read2_b32 v[26:27], v11 offset0:99 offset1:107
	ds_read2_b32 v[28:29], v11 offset0:132 offset1:140
	ds_read2_b32 v[30:31], v11 offset0:165 offset1:173
	ds_read2_b32 v[32:33], v11 offset0:198 offset1:206
	ds_read2_b32 v[34:35], v11 offset0:231 offset1:239
	v_lshl_add_u64 v[18:19], s[56:57], 0, v[18:19]
	v_mov_b32_e32 v17, v13
	v_lshl_add_u64 v[16:17], v[16:17], 1, v[18:19]
	v_lshlrev_b32_e32 v12, 1, v14
	v_lshl_add_u64 v[36:37], v[16:17], 0, v[12:13]
	v_or_b32_e32 v12, v40, v7
	v_lshlrev_b32_e32 v12, 12, v12
	s_waitcnt lgkmcnt(6)
	v_cvt_pk_bf16_f32 v16, v22, v20
	s_waitcnt lgkmcnt(4)
	v_cvt_pk_bf16_f32 v17, v24, v26
	s_waitcnt lgkmcnt(2)
	v_cvt_pk_bf16_f32 v18, v28, v30
	s_waitcnt lgkmcnt(0)
	v_cvt_pk_bf16_f32 v19, v32, v34
	v_lshl_add_u64 v[38:39], v[36:37], 0, v[12:13]
	global_store_dwordx4 v[38:39], v[16:19], off nt
	v_or_b32_e32 v12, v40, v15
	v_lshlrev_b32_e32 v12, 12, v12
	v_cvt_pk_bf16_f32 v16, v23, v21
	v_cvt_pk_bf16_f32 v17, v25, v27
	v_cvt_pk_bf16_f32 v18, v29, v31
	v_cvt_pk_bf16_f32 v19, v33, v35
	ds_read2_b32 v[22:23], v11 offset0:49 offset1:57
	ds_read2_b32 v[24:25], v11 offset0:16 offset1:24
	ds_read2_b32 v[26:27], v11 offset0:82 offset1:90
	ds_read2_b32 v[28:29], v11 offset0:115 offset1:123
	ds_read2_b32 v[30:31], v11 offset0:148 offset1:156
	ds_read2_b32 v[32:33], v11 offset0:181 offset1:189
	ds_read2_b32 v[34:35], v11 offset0:214 offset1:222
	ds_read2_b32 v[38:39], v11 offset0:247 offset1:255
	v_lshl_add_u64 v[20:21], v[36:37], 0, v[12:13]
	v_or_b32_e32 v12, v40, v56
	v_lshlrev_b32_e32 v12, 12, v12
	global_store_dwordx4 v[20:21], v[16:19], off nt
	v_lshl_add_u64 v[20:21], v[36:37], 0, v[12:13]
	v_or_b32_e32 v12, v40, v57
	s_waitcnt lgkmcnt(6)
	v_cvt_pk_bf16_f32 v16, v24, v22
	s_waitcnt lgkmcnt(4)
	v_cvt_pk_bf16_f32 v17, v26, v28
	s_waitcnt lgkmcnt(2)
	v_cvt_pk_bf16_f32 v18, v30, v32
	s_waitcnt lgkmcnt(0)
	v_cvt_pk_bf16_f32 v19, v34, v38
	v_lshlrev_b32_e32 v12, 12, v12
	global_store_dwordx4 v[20:21], v[16:19], off nt
	v_lshl_add_u64 v[20:21], v[36:37], 0, v[12:13]
	s_nop 0
	v_cvt_pk_bf16_f32 v16, v25, v23
	v_cvt_pk_bf16_f32 v17, v27, v29
	v_cvt_pk_bf16_f32 v18, v31, v33
	v_cvt_pk_bf16_f32 v19, v35, v39
	global_store_dwordx4 v[20:21], v[16:19], off nt
	s_waitcnt lgkmcnt(0)
.LBB0_20:
	s_andn2_saveexec_b64 s[44:45], s[44:45]
	s_cbranch_execz .LBB0_22
	v_lshlrev_b64 v[16:17], 21, v[20:21]
	v_lshl_add_u64 v[18:19], s[48:49], 0, v[16:17]
	v_and_b32_e32 v16, 0x7fc0, v12
	v_lshlrev_b32_e32 v12, 5, v12
	v_and_b32_e32 v40, 0x7e0, v12
	v_add_u32_e32 v16, 0xffff8200, v16
	v_lshlrev_b32_e32 v12, 2, v40
	v_or_b32_e32 v22, v16, v8
	v_lshl_add_u64 v[18:19], v[18:19], 0, v[12:13]
	v_lshlrev_b32_e32 v12, 2, v10
	v_lshl_add_u64 v[18:19], v[18:19], 0, v[12:13]
	v_or_b32_e32 v12, 2, v22
	v_lshlrev_b64 v[26:27], 13, v[12:13]
	v_or_b32_e32 v12, 4, v22
	v_lshlrev_b64 v[28:29], 13, v[12:13]
	v_or_b32_e32 v12, 6, v22
	v_lshlrev_b64 v[30:31], 13, v[12:13]
	v_or_b32_e32 v12, 8, v22
	v_lshlrev_b64 v[32:33], 13, v[12:13]
	v_or_b32_e32 v12, 10, v22
	v_mov_b32_e32 v23, v13
	v_lshlrev_b64 v[34:35], 13, v[12:13]
	v_or_b32_e32 v12, 12, v22
	v_lshlrev_b64 v[24:25], 13, v[22:23]
	v_lshlrev_b64 v[36:37], 13, v[12:13]
	v_or_b32_e32 v12, 14, v22
	v_lshl_add_u64 v[24:25], v[18:19], 0, v[24:25]
	v_lshlrev_b64 v[38:39], 13, v[12:13]
	v_or_b32_e32 v12, 16, v22
	v_lshl_add_u64 v[26:27], v[18:19], 0, v[26:27]
	v_lshl_add_u64 v[28:29], v[18:19], 0, v[28:29]
	v_lshl_add_u64 v[30:31], v[18:19], 0, v[30:31]
	v_lshl_add_u64 v[32:33], v[18:19], 0, v[32:33]
	v_lshl_add_u64 v[34:35], v[18:19], 0, v[34:35]
	v_lshl_add_u64 v[36:37], v[18:19], 0, v[36:37]
	v_lshl_add_u64 v[38:39], v[18:19], 0, v[38:39]
	global_load_dword v17, v[24:25], off
	global_load_dword v41, v[26:27], off
	global_load_dword v42, v[28:29], off
	global_load_dword v43, v[30:31], off
	global_load_dword v44, v[32:33], off
	global_load_dword v45, v[34:35], off
	global_load_dword v46, v[36:37], off
	global_load_dword v47, v[38:39], off
	v_lshlrev_b64 v[24:25], 13, v[12:13]
	v_or_b32_e32 v12, 18, v22
	v_lshlrev_b64 v[26:27], 13, v[12:13]
	v_or_b32_e32 v12, 20, v22
	v_lshlrev_b64 v[28:29], 13, v[12:13]
; __device__ __forceinline__ void transpose_item(const float* W, int ldw, const float* kgain, float scale, bf16_t* WT, int ldt, int k0, int n_src0, int n_dst0, LAS float* scr, int lane) {
;     ...
;     for (int i = 0; i < 32; ++i) wv[i] = W[(size_t)(k0 + 2 * i + (lane >> 5)) * ldw + n_src0 + (lane & 31)];
;     if (kgain) {
; #pragma unroll
;         for (int i = 0; i < 32; ++i) wv[i] *= kgain[k0 + 2 * i + (lane >> 5)] * scale; }
; #pragma unroll
;     for (int i = 0; i < 32; ++i) scr[(2 * i + (lane >> 5)) * 33 + (lane & 31)] = wv[i];
	v_or_b32_e32 v12, 22, v22
	v_lshlrev_b64 v[30:31], 13, v[12:13]
	v_or_b32_e32 v12, 24, v22
	v_lshlrev_b64 v[32:33], 13, v[12:13]
	v_or_b32_e32 v12, 26, v22
	v_lshlrev_b64 v[34:35], 13, v[12:13]
	v_or_b32_e32 v12, 28, v22
	v_lshlrev_b64 v[36:37], 13, v[12:13]
	v_or_b32_e32 v12, 30, v22
	v_lshl_add_u64 v[24:25], v[18:19], 0, v[24:25]
	v_lshlrev_b64 v[38:39], 13, v[12:13]
	v_or_b32_e32 v12, 32, v22
	v_lshl_add_u64 v[26:27], v[18:19], 0, v[26:27]
	v_lshl_add_u64 v[28:29], v[18:19], 0, v[28:29]
	v_lshl_add_u64 v[30:31], v[18:19], 0, v[30:31]
	v_lshl_add_u64 v[32:33], v[18:19], 0, v[32:33]
	v_lshl_add_u64 v[34:35], v[18:19], 0, v[34:35]
	v_lshl_add_u64 v[36:37], v[18:19], 0, v[36:37]
	v_lshl_add_u64 v[38:39], v[18:19], 0, v[38:39]
	global_load_dword v48, v[24:25], off
	global_load_dword v49, v[26:27], off
	global_load_dword v50, v[28:29], off
	global_load_dword v51, v[30:31], off
	global_load_dword v52, v[32:33], off
	global_load_dword v53, v[34:35], off
	global_load_dword v54, v[36:37], off
	global_load_dword v55, v[38:39], off
	v_lshlrev_b64 v[24:25], 13, v[12:13]
	v_or_b32_e32 v12, 34, v22
	v_lshlrev_b64 v[26:27], 13, v[12:13]
	v_or_b32_e32 v12, 36, v22
	v_lshlrev_b64 v[28:29], 13, v[12:13]
	v_or_b32_e32 v12, 38, v22
	v_lshlrev_b64 v[30:31], 13, v[12:13]
	v_or_b32_e32 v12, 40, v22
	v_lshlrev_b64 v[32:33], 13, v[12:13]
	v_or_b32_e32 v12, 42, v22
	v_lshlrev_b64 v[34:35], 13, v[12:13]
	v_or_b32_e32 v12, 44, v22
	v_lshlrev_b64 v[36:37], 13, v[12:13]
	v_or_b32_e32 v12, 46, v22
	v_lshlrev_b64 v[38:39], 13, v[12:13]
	v_lshl_add_u64 v[24:25], v[18:19], 0, v[24:25]
	v_lshl_add_u64 v[38:39], v[18:19], 0, v[38:39]
	v_or_b32_e32 v12, 48, v22
	v_lshl_add_u64 v[26:27], v[18:19], 0, v[26:27]
	v_lshl_add_u64 v[28:29], v[18:19], 0, v[28:29]
	v_lshl_add_u64 v[30:31], v[18:19], 0, v[30:31]
	v_lshl_add_u64 v[32:33], v[18:19], 0, v[32:33]
	v_lshl_add_u64 v[34:35], v[18:19], 0, v[34:35]
	v_lshl_add_u64 v[36:37], v[18:19], 0, v[36:37]
	global_load_dword v69, v[24:25], off
	global_load_dword v70, v[26:27], off
	global_load_dword v71, v[28:29], off
	global_load_dword v72, v[30:31], off
	global_load_dword v73, v[32:33], off
	global_load_dword v74, v[34:35], off
	global_load_dword v75, v[36:37], off
	s_nop 0
	global_load_dword v38, v[38:39], off
	v_lshlrev_b64 v[24:25], 13, v[12:13]
	v_or_b32_e32 v12, 50, v22
	v_lshlrev_b64 v[26:27], 13, v[12:13]
	v_or_b32_e32 v12, 52, v22
	v_lshlrev_b64 v[28:29], 13, v[12:13]
	v_or_b32_e32 v12, 54, v22
	v_lshlrev_b64 v[30:31], 13, v[12:13]
	v_or_b32_e32 v12, 56, v22
	v_lshlrev_b64 v[32:33], 13, v[12:13]
	v_or_b32_e32 v12, 58, v22
	v_lshlrev_b64 v[34:35], 13, v[12:13]
	v_or_b32_e32 v12, 60, v22
	v_lshlrev_b64 v[36:37], 13, v[12:13]
	v_or_b32_e32 v12, 62, v22
	v_lshl_add_u64 v[24:25], v[18:19], 0, v[24:25]
	v_lshl_add_u64 v[26:27], v[18:19], 0, v[26:27]
	v_lshl_add_u64 v[28:29], v[18:19], 0, v[28:29]
	v_lshlrev_b64 v[22:23], 13, v[12:13]
	v_lshl_add_u64 v[30:31], v[18:19], 0, v[30:31]
	v_lshl_add_u64 v[32:33], v[18:19], 0, v[32:33]
	v_lshl_add_u64 v[34:35], v[18:19], 0, v[34:35]
	v_lshl_add_u64 v[36:37], v[18:19], 0, v[36:37]
	v_lshl_add_u64 v[18:19], v[18:19], 0, v[22:23]
	global_load_dword v12, v[24:25], off
	global_load_dword v22, v[26:27], off
	global_load_dword v23, v[28:29], off
	s_nop 0
	global_load_dword v24, v[30:31], off
	global_load_dword v25, v[32:33], off
	global_load_dword v26, v[34:35], off
	global_load_dword v27, v[36:37], off
	global_load_dword v28, v[18:19], off
	s_waitcnt vmcnt(30)
	ds_write2_b32 v5, v17, v41 offset1:66
	s_waitcnt vmcnt(28)
	ds_write2_b32 v5, v42, v43 offset0:132 offset1:198
	v_add_u32_e32 v17, 0x400, v5
	s_waitcnt vmcnt(26)
; #define LAS __attribute__((address_space(3)))
; __device__ __forceinline__ unsigned pk2(float lo, float hi) { return pg8::cvt_pk_bf16(lo, hi); }
; __device__ __forceinline__ void transpose_item(const float* W, int ldw, const float* kgain, float scale, bf16_t* WT, int ldt, int k0, int n_src0, int n_dst0, LAS float* scr, int lane) {
;     ...
;     for (int i = 0; i < 32; ++i) scr[(2 * i + (lane >> 5)) * 33 + (lane & 31)] = wv[i];
;     asm volatile("s_waitcnt lgkmcnt(0)" ::: "memory");
;     const int c = lane & 7;
; #pragma unroll
;     for (int j = 0; j < 4; ++j) { const int n = (lane >> 3) + 8 * j; const LAS float* s = scr + (8 * c) * 33 + n;
;         u32x4 o; o.x = pk2(s[0 * 33], s[1 * 33]); o.y = pk2(s[2 * 33], s[3 * 33]); o.z = pk2(s[4 * 33], s[5 * 33]); o.w = pk2(s[6 * 33], s[7 * 33]);
;         *(u32x4*)(WT + (size_t)(n_dst0 + n) * ldt + k0 + 8 * c) = o; }
;     asm volatile("s_waitcnt lgkmcnt(0)" ::: "memory");
	ds_write2_b32 v17, v44, v45 offset0:8 offset1:74
	s_waitcnt vmcnt(24)
	ds_write2_b32 v17, v46, v47 offset0:140 offset1:206
	v_add_u32_e32 v17, 0x800, v5
	s_waitcnt vmcnt(22)
	ds_write2_b32 v17, v48, v49 offset0:16 offset1:82
	s_waitcnt vmcnt(20)
	ds_write2_b32 v17, v50, v51 offset0:148 offset1:214
	v_add_u32_e32 v17, 0xc00, v5
	s_waitcnt vmcnt(18)
	ds_write2_b32 v17, v52, v53 offset0:24 offset1:90
	s_waitcnt vmcnt(16)
	ds_write2_b32 v17, v54, v55 offset0:156 offset1:222
	v_add_u32_e32 v17, 0x1000, v5
	s_waitcnt vmcnt(14)
	ds_write2_b32 v17, v69, v70 offset0:32 offset1:98
	s_waitcnt vmcnt(12)
	ds_write2_b32 v17, v71, v72 offset0:164 offset1:230
	v_add_u32_e32 v17, 0x1400, v5
	s_waitcnt vmcnt(10)
	ds_write2_b32 v17, v73, v74 offset0:40 offset1:106
	s_waitcnt vmcnt(8)
	ds_write2_b32 v17, v75, v38 offset0:172 offset1:238
	v_add_u32_e32 v17, 0x1800, v5
	s_waitcnt vmcnt(6)
	ds_write2_b32 v17, v12, v22 offset0:48 offset1:114
	s_waitcnt vmcnt(4)
	ds_write2_b32 v17, v23, v24 offset0:180 offset1:246
	v_add_u32_e32 v12, 0x1c00, v5
	s_waitcnt vmcnt(2)
	ds_write2_b32 v12, v25, v26 offset0:56 offset1:122
	s_waitcnt vmcnt(0)
	ds_write2_b32 v12, v27, v28 offset0:188 offset1:254
	s_waitcnt lgkmcnt(0)
	v_lshlrev_b64 v[18:19], 20, v[20:21]
	ds_read2_b32 v[20:21], v11 offset0:33 offset1:41
	ds_read2_b32 v[22:23], v11 offset1:8
	ds_read2_b32 v[24:25], v11 offset0:66 offset1:74
	ds_read2_b32 v[26:27], v11 offset0:99 offset1:107
	ds_read2_b32 v[28:29], v11 offset0:132 offset1:140
	ds_read2_b32 v[30:31], v11 offset0:165 offset1:173
	ds_read2_b32 v[32:33], v11 offset0:198 offset1:206
	ds_read2_b32 v[34:35], v11 offset0:231 offset1:239
	v_lshl_add_u64 v[18:19], s[58:59], 0, v[18:19]
	v_mov_b32_e32 v17, v13
	v_lshl_add_u64 v[16:17], v[16:17], 1, v[18:19]
	v_lshlrev_b32_e32 v12, 1, v14
	v_lshl_add_u64 v[36:37], v[16:17], 0, v[12:13]
	v_or_b32_e32 v12, v40, v7
	v_lshlrev_b32_e32 v12, 9, v12
	s_waitcnt lgkmcnt(6)
	v_cvt_pk_bf16_f32 v16, v22, v20
	s_waitcnt lgkmcnt(4)
	v_cvt_pk_bf16_f32 v17, v24, v26
	s_waitcnt lgkmcnt(2)
	v_cvt_pk_bf16_f32 v18, v28, v30
	s_waitcnt lgkmcnt(0)
	v_cvt_pk_bf16_f32 v19, v32, v34
	v_lshl_add_u64 v[38:39], v[36:37], 0, v[12:13]
	global_store_dwordx4 v[38:39], v[16:19], off nt
	v_or_b32_e32 v12, v40, v15
	v_lshlrev_b32_e32 v12, 9, v12
	v_cvt_pk_bf16_f32 v16, v23, v21
	v_cvt_pk_bf16_f32 v17, v25, v27
	v_cvt_pk_bf16_f32 v18, v29, v31
	v_cvt_pk_bf16_f32 v19, v33, v35
	ds_read2_b32 v[22:23], v11 offset0:49 offset1:57
	ds_read2_b32 v[24:25], v11 offset0:16 offset1:24
	ds_read2_b32 v[26:27], v11 offset0:82 offset1:90
	ds_read2_b32 v[28:29], v11 offset0:115 offset1:123
	ds_read2_b32 v[30:31], v11 offset0:148 offset1:156
	ds_read2_b32 v[32:33], v11 offset0:181 offset1:189
	ds_read2_b32 v[34:35], v11 offset0:214 offset1:222
	ds_read2_b32 v[38:39], v11 offset0:247 offset1:255
	v_lshl_add_u64 v[20:21], v[36:37], 0, v[12:13]
	v_or_b32_e32 v12, v40, v56
	v_lshlrev_b32_e32 v12, 9, v12
	global_store_dwordx4 v[20:21], v[16:19], off nt
	v_lshl_add_u64 v[20:21], v[36:37], 0, v[12:13]
	v_or_b32_e32 v12, v40, v57
	s_waitcnt lgkmcnt(6)
	v_cvt_pk_bf16_f32 v16, v24, v22
	s_waitcnt lgkmcnt(4)
	v_cvt_pk_bf16_f32 v17, v26, v28
	s_waitcnt lgkmcnt(2)
	v_cvt_pk_bf16_f32 v18, v30, v32
	s_waitcnt lgkmcnt(0)
	v_cvt_pk_bf16_f32 v19, v34, v38
	v_lshlrev_b32_e32 v12, 9, v12
	global_store_dwordx4 v[20:21], v[16:19], off nt
	v_lshl_add_u64 v[20:21], v[36:37], 0, v[12:13]
	s_nop 0
	v_cvt_pk_bf16_f32 v16, v25, v23
	v_cvt_pk_bf16_f32 v17, v27, v29
	v_cvt_pk_bf16_f32 v18, v31, v33
	v_cvt_pk_bf16_f32 v19, v35, v39
	global_store_dwordx4 v[20:21], v[16:19], off nt
	s_waitcnt lgkmcnt(0)

; __device__ __forceinline__ void transpose_item(const float* W, int ldw, const float* kgain, float scale, bf16_t* WT, int ldt, int k0, int n_src0, int n_dst0, LAS float* scr, int lane) {
;     float wv[32];
; #pragma unroll
;     for (int i = 0; i < 32; ++i) wv[i] = W[(size_t)(k0 + 2 * i + (lane >> 5)) * ldw + n_src0 + (lane & 31)];
; __device__ __forceinline__ void phase_prologue(const P& p, unsigned char* ws, LAS unsigned char* lds, int wg, int nwg) {
;     ...
;         if (r < I_F2) { transpose_item(p.w_ff2 + (size_t)l * DFF * D, D, nullptr, 1.f, (bf16_t*)(ws + WS_WFF2) + (size_t)l * D * DFF, DFF, (r / (D / 32)) * 64, (r % (D / 32)) * 32, (r % (D / 32)) * 32, scr, lane); continue; } r -= I_F2;
.LBB0_23:
	s_andn2_saveexec_b64 s[44:45], s[90:91]
	s_cbranch_execz .LBB0_25
	v_lshlrev_b64 v[16:17], 26, v[20:21]
	v_lshl_add_u64 v[18:19], s[46:47], 0, v[16:17]
	v_and_b32_e32 v16, 0x7fc0, v12
	v_lshlrev_b32_e32 v12, 5, v12
	v_and_b32_e32 v40, 0x7e0, v12
	v_add_u32_e32 v16, 0xffffa200, v16
	v_lshlrev_b32_e32 v12, 2, v40
	v_or_b32_e32 v22, v16, v8
	v_lshl_add_u64 v[18:19], v[18:19], 0, v[12:13]
	v_lshlrev_b32_e32 v12, 2, v10
	v_lshl_add_u64 v[18:19], v[18:19], 0, v[12:13]
	v_or_b32_e32 v12, 2, v22
	v_lshlrev_b64 v[26:27], 13, v[12:13]
	v_or_b32_e32 v12, 4, v22
	v_lshlrev_b64 v[28:29], 13, v[12:13]
	v_or_b32_e32 v12, 6, v22
	v_lshlrev_b64 v[30:31], 13, v[12:13]
	v_or_b32_e32 v12, 8, v22
	v_lshlrev_b64 v[32:33], 13, v[12:13]
	v_or_b32_e32 v12, 10, v22
	v_mov_b32_e32 v23, v13
	v_lshlrev_b64 v[34:35], 13, v[12:13]
	v_or_b32_e32 v12, 12, v22
	v_lshlrev_b64 v[24:25], 13, v[22:23]
	v_lshlrev_b64 v[36:37], 13, v[12:13]
	v_or_b32_e32 v12, 14, v22
	v_lshl_add_u64 v[24:25], v[18:19], 0, v[24:25]
	v_lshlrev_b64 v[38:39], 13, v[12:13]
	v_or_b32_e32 v12, 16, v22
	v_lshl_add_u64 v[26:27], v[18:19], 0, v[26:27]
	v_lshl_add_u64 v[28:29], v[18:19], 0, v[28:29]
	v_lshl_add_u64 v[30:31], v[18:19], 0, v[30:31]
	v_lshl_add_u64 v[32:33], v[18:19], 0, v[32:33]
	v_lshl_add_u64 v[34:35], v[18:19], 0, v[34:35]
	v_lshl_add_u64 v[36:37], v[18:19], 0, v[36:37]
	v_lshl_add_u64 v[38:39], v[18:19], 0, v[38:39]
	global_load_dword v17, v[24:25], off
	global_load_dword v41, v[26:27], off
	global_load_dword v42, v[28:29], off
	global_load_dword v43, v[30:31], off
	global_load_dword v44, v[32:33], off
	global_load_dword v45, v[34:35], off
	global_load_dword v46, v[36:37], off
	global_load_dword v47, v[38:39], off
	v_lshlrev_b64 v[24:25], 13, v[12:13]
	v_or_b32_e32 v12, 18, v22
	v_lshlrev_b64 v[26:27], 13, v[12:13]
	v_or_b32_e32 v12, 20, v22
	v_lshlrev_b64 v[28:29], 13, v[12:13]
	v_or_b32_e32 v12, 22, v22
	v_lshlrev_b64 v[30:31], 13, v[12:13]
	v_or_b32_e32 v12, 24, v22
	v_lshlrev_b64 v[32:33], 13, v[12:13]
	v_or_b32_e32 v12, 26, v22
	v_lshlrev_b64 v[34:35], 13, v[12:13]
	v_or_b32_e32 v12, 28, v22
	v_lshlrev_b64 v[36:37], 13, v[12:13]
	v_or_b32_e32 v12, 30, v22
	v_lshl_add_u64 v[24:25], v[18:19], 0, v[24:25]
	v_lshlrev_b64 v[38:39], 13, v[12:13]
	v_or_b32_e32 v12, 32, v22
	v_lshl_add_u64 v[26:27], v[18:19], 0, v[26:27]
	v_lshl_add_u64 v[28:29], v[18:19], 0, v[28:29]
	v_lshl_add_u64 v[30:31], v[18:19], 0, v[30:31]
	v_lshl_add_u64 v[32:33], v[18:19], 0, v[32:33]
	v_lshl_add_u64 v[34:35], v[18:19], 0, v[34:35]
	v_lshl_add_u64 v[36:37], v[18:19], 0, v[36:37]
	v_lshl_add_u64 v[38:39], v[18:19], 0, v[38:39]
	global_load_dword v48, v[24:25], off
	global_load_dword v49, v[26:27], off
	global_load_dword v50, v[28:29], off
	global_load_dword v51, v[30:31], off
	global_load_dword v52, v[32:33], off
	global_load_dword v53, v[34:35], off
	global_load_dword v54, v[36:37], off
	global_load_dword v55, v[38:39], off
	v_lshlrev_b64 v[24:25], 13, v[12:13]
	v_or_b32_e32 v12, 34, v22
	v_lshlrev_b64 v[26:27], 13, v[12:13]
	v_or_b32_e32 v12, 36, v22
	v_lshlrev_b64 v[28:29], 13, v[12:13]
	v_or_b32_e32 v12, 38, v22
	v_lshlrev_b64 v[30:31], 13, v[12:13]
	v_or_b32_e32 v12, 40, v22
	v_lshlrev_b64 v[32:33], 13, v[12:13]
	v_or_b32_e32 v12, 42, v22
	v_lshlrev_b64 v[34:35], 13, v[12:13]
	v_or_b32_e32 v12, 44, v22
	v_lshlrev_b64 v[36:37], 13, v[12:13]
	v_or_b32_e32 v12, 46, v22
	v_lshlrev_b64 v[38:39], 13, v[12:13]
	v_lshl_add_u64 v[24:25], v[18:19], 0, v[24:25]
	v_lshl_add_u64 v[38:39], v[18:19], 0, v[38:39]
	v_or_b32_e32 v12, 48, v22
	v_lshl_add_u64 v[26:27], v[18:19], 0, v[26:27]
	v_lshl_add_u64 v[28:29], v[18:19], 0, v[28:29]
	v_lshl_add_u64 v[30:31], v[18:19], 0, v[30:31]
	v_lshl_add_u64 v[32:33], v[18:19], 0, v[32:33]
	v_lshl_add_u64 v[34:35], v[18:19], 0, v[34:35]
	v_lshl_add_u64 v[36:37], v[18:19], 0, v[36:37]
	global_load_dword v69, v[24:25], off
	global_load_dword v70, v[26:27], off
	global_load_dword v71, v[28:29], off
	global_load_dword v72, v[30:31], off
	global_load_dword v73, v[32:33], off
	global_load_dword v74, v[34:35], off
	global_load_dword v75, v[36:37], off
	s_nop 0
	global_load_dword v38, v[38:39], off
	v_lshlrev_b64 v[24:25], 13, v[12:13]
	v_or_b32_e32 v12, 50, v22
	v_lshlrev_b64 v[26:27], 13, v[12:13]
	v_or_b32_e32 v12, 52, v22
	v_lshlrev_b64 v[28:29], 13, v[12:13]
	v_or_b32_e32 v12, 54, v22
	v_lshlrev_b64 v[30:31], 13, v[12:13]
	v_or_b32_e32 v12, 56, v22
	v_lshlrev_b64 v[32:33], 13, v[12:13]
	v_or_b32_e32 v12, 58, v22
	v_lshlrev_b64 v[34:35], 13, v[12:13]
	v_or_b32_e32 v12, 60, v22
	v_lshlrev_b64 v[36:37], 13, v[12:13]
	v_or_b32_e32 v12, 62, v22
	v_lshl_add_u64 v[24:25], v[18:19], 0, v[24:25]
	v_lshl_add_u64 v[26:27], v[18:19], 0, v[26:27]
	v_lshl_add_u64 v[28:29], v[18:19], 0, v[28:29]
	v_lshlrev_b64 v[22:23], 13, v[12:13]
	v_lshl_add_u64 v[30:31], v[18:19], 0, v[30:31]
	v_lshl_add_u64 v[32:33], v[18:19], 0, v[32:33]
	v_lshl_add_u64 v[34:35], v[18:19], 0, v[34:35]
	v_lshl_add_u64 v[36:37], v[18:19], 0, v[36:37]
	v_lshl_add_u64 v[18:19], v[18:19], 0, v[22:23]
	global_load_dword v12, v[24:25], off
	global_load_dword v22, v[26:27], off
	global_load_dword v23, v[28:29], off
	s_nop 0
	global_load_dword v24, v[30:31], off
	global_load_dword v25, v[32:33], off
	global_load_dword v26, v[34:35], off
	global_load_dword v27, v[36:37], off
	global_load_dword v28, v[18:19], off
	s_waitcnt vmcnt(30)
; #define LAS __attribute__((address_space(3)))
; __device__ __forceinline__ unsigned pk2(float lo, float hi) { return pg8::cvt_pk_bf16(lo, hi); }
; __device__ __forceinline__ void transpose_item(const float* W, int ldw, const float* kgain, float scale, bf16_t* WT, int ldt, int k0, int n_src0, int n_dst0, LAS float* scr, int lane) {
;     ...
;     for (int i = 0; i < 32; ++i) scr[(2 * i + (lane >> 5)) * 33 + (lane & 31)] = wv[i];
;     asm volatile("s_waitcnt lgkmcnt(0)" ::: "memory");
;     const int c = lane & 7;
; #pragma unroll
;     for (int j = 0; j < 4; ++j) { const int n = (lane >> 3) + 8 * j; const LAS float* s = scr + (8 * c) * 33 + n;
;         u32x4 o; o.x = pk2(s[0 * 33], s[1 * 33]); o.y = pk2(s[2 * 33], s[3 * 33]); o.z = pk2(s[4 * 33], s[5 * 33]); o.w = pk2(s[6 * 33], s[7 * 33]);
;         *(u32x4*)(WT + (size_t)(n_dst0 + n) * ldt + k0 + 8 * c) = o; }
;     asm volatile("s_waitcnt lgkmcnt(0)" ::: "memory");
	ds_write2_b32 v5, v17, v41 offset1:66
	s_waitcnt vmcnt(28)
	ds_write2_b32 v5, v42, v43 offset0:132 offset1:198
	v_add_u32_e32 v17, 0x400, v5
	s_waitcnt vmcnt(26)
	ds_write2_b32 v17, v44, v45 offset0:8 offset1:74
	s_waitcnt vmcnt(24)
	ds_write2_b32 v17, v46, v47 offset0:140 offset1:206
	v_add_u32_e32 v17, 0x800, v5
	s_waitcnt vmcnt(22)
	ds_write2_b32 v17, v48, v49 offset0:16 offset1:82
	s_waitcnt vmcnt(20)
	ds_write2_b32 v17, v50, v51 offset0:148 offset1:214
	v_add_u32_e32 v17, 0xc00, v5
	s_waitcnt vmcnt(18)
	ds_write2_b32 v17, v52, v53 offset0:24 offset1:90
	s_waitcnt vmcnt(16)
	ds_write2_b32 v17, v54, v55 offset0:156 offset1:222
	v_add_u32_e32 v17, 0x1000, v5
	s_waitcnt vmcnt(14)
	ds_write2_b32 v17, v69, v70 offset0:32 offset1:98
	s_waitcnt vmcnt(12)
	ds_write2_b32 v17, v71, v72 offset0:164 offset1:230
	v_add_u32_e32 v17, 0x1400, v5
	s_waitcnt vmcnt(10)
	ds_write2_b32 v17, v73, v74 offset0:40 offset1:106
	s_waitcnt vmcnt(8)
	ds_write2_b32 v17, v75, v38 offset0:172 offset1:238
	v_add_u32_e32 v17, 0x1800, v5
	s_waitcnt vmcnt(6)
	ds_write2_b32 v17, v12, v22 offset0:48 offset1:114
	s_waitcnt vmcnt(4)
	ds_write2_b32 v17, v23, v24 offset0:180 offset1:246
	v_add_u32_e32 v12, 0x1c00, v5
	s_waitcnt vmcnt(2)
	ds_write2_b32 v12, v25, v26 offset0:56 offset1:122
	s_waitcnt vmcnt(0)
	ds_write2_b32 v12, v27, v28 offset0:188 offset1:254
	s_waitcnt lgkmcnt(0)
	v_lshlrev_b64 v[18:19], 25, v[20:21]
	ds_read2_b32 v[20:21], v11 offset0:33 offset1:41
	ds_read2_b32 v[22:23], v11 offset1:8
	ds_read2_b32 v[24:25], v11 offset0:66 offset1:74
	ds_read2_b32 v[26:27], v11 offset0:99 offset1:107
	ds_read2_b32 v[28:29], v11 offset0:132 offset1:140
	ds_read2_b32 v[30:31], v11 offset0:165 offset1:173
	ds_read2_b32 v[32:33], v11 offset0:198 offset1:206
	ds_read2_b32 v[34:35], v11 offset0:231 offset1:239
	v_lshl_add_u64 v[18:19], s[60:61], 0, v[18:19]
	v_mov_b32_e32 v17, v13
	v_lshl_add_u64 v[16:17], v[16:17], 1, v[18:19]
	v_lshlrev_b32_e32 v12, 1, v14
	v_lshl_add_u64 v[36:37], v[16:17], 0, v[12:13]
	v_or_b32_e32 v12, v40, v7
	v_lshlrev_b32_e32 v12, 14, v12
	s_waitcnt lgkmcnt(6)
	v_cvt_pk_bf16_f32 v16, v22, v20
	s_waitcnt lgkmcnt(4)
	v_cvt_pk_bf16_f32 v17, v24, v26
	s_waitcnt lgkmcnt(2)
	v_cvt_pk_bf16_f32 v18, v28, v30
	s_waitcnt lgkmcnt(0)
	v_cvt_pk_bf16_f32 v19, v32, v34
	v_lshl_add_u64 v[38:39], v[36:37], 0, v[12:13]
	global_store_dwordx4 v[38:39], v[16:19], off nt
	v_or_b32_e32 v12, v40, v15
	v_lshlrev_b32_e32 v12, 14, v12
	v_cvt_pk_bf16_f32 v16, v23, v21
	v_cvt_pk_bf16_f32 v17, v25, v27
	v_cvt_pk_bf16_f32 v18, v29, v31
	v_cvt_pk_bf16_f32 v19, v33, v35
	ds_read2_b32 v[22:23], v11 offset0:49 offset1:57
	ds_read2_b32 v[24:25], v11 offset0:16 offset1:24
	ds_read2_b32 v[26:27], v11 offset0:82 offset1:90
	ds_read2_b32 v[28:29], v11 offset0:115 offset1:123
	ds_read2_b32 v[30:31], v11 offset0:148 offset1:156
	ds_read2_b32 v[32:33], v11 offset0:181 offset1:189
	ds_read2_b32 v[34:35], v11 offset0:214 offset1:222
	ds_read2_b32 v[38:39], v11 offset0:247 offset1:255
	v_lshl_add_u64 v[20:21], v[36:37], 0, v[12:13]
	v_or_b32_e32 v12, v40, v56
	v_lshlrev_b32_e32 v12, 14, v12
	global_store_dwordx4 v[20:21], v[16:19], off nt
	v_lshl_add_u64 v[20:21], v[36:37], 0, v[12:13]
	v_or_b32_e32 v12, v40, v57
	s_waitcnt lgkmcnt(6)
	v_cvt_pk_bf16_f32 v16, v24, v22
	s_waitcnt lgkmcnt(4)
	v_cvt_pk_bf16_f32 v17, v26, v28
	s_waitcnt lgkmcnt(2)
	v_cvt_pk_bf16_f32 v18, v30, v32
	s_waitcnt lgkmcnt(0)
	v_cvt_pk_bf16_f32 v19, v34, v38
	v_lshlrev_b32_e32 v12, 14, v12
	global_store_dwordx4 v[20:21], v[16:19], off nt
	v_lshl_add_u64 v[20:21], v[36:37], 0, v[12:13]
	s_nop 0
	v_cvt_pk_bf16_f32 v16, v25, v23
	v_cvt_pk_bf16_f32 v17, v27, v29
	v_cvt_pk_bf16_f32 v18, v31, v33
	v_cvt_pk_bf16_f32 v19, v35, v39
	global_store_dwordx4 v[20:21], v[16:19], off nt
	s_waitcnt lgkmcnt(0)

; #define LAS __attribute__((address_space(3)))
; __device__ __forceinline__ unsigned pk2(float lo, float hi) { return pg8::cvt_pk_bf16(lo, hi); }
; __device__ __forceinline__ void transpose_item(const float* W, int ldw, const float* kgain, float scale, bf16_t* WT, int ldt, int k0, int n_src0, int n_dst0, LAS float* scr, int lane) {
;     ...
;     for (int i = 0; i < 32; ++i) scr[(2 * i + (lane >> 5)) * 33 + (lane & 31)] = wv[i];
;     asm volatile("s_waitcnt lgkmcnt(0)" ::: "memory");
;     const int c = lane & 7;
; #pragma unroll
;     for (int j = 0; j < 4; ++j) { const int n = (lane >> 3) + 8 * j; const LAS float* s = scr + (8 * c) * 33 + n;
;         u32x4 o; o.x = pk2(s[0 * 33], s[1 * 33]); o.y = pk2(s[2 * 33], s[3 * 33]); o.z = pk2(s[4 * 33], s[5 * 33]); o.w = pk2(s[6 * 33], s[7 * 33]);
;         *(u32x4*)(WT + (size_t)(n_dst0 + n) * ldt + k0 + 8 * c) = o; }
;     asm volatile("s_waitcnt lgkmcnt(0)" ::: "memory");
.LBB0_29:
	v_add_u32_e32 v12, 0x400, v5
	s_waitcnt vmcnt(30)
	ds_write2_b32 v5, v16, v17 offset1:66
	s_waitcnt vmcnt(28)
	ds_write2_b32 v5, v22, v23 offset0:132 offset1:198
	s_waitcnt vmcnt(26)
	ds_write2_b32 v12, v18, v19 offset0:8 offset1:74
	s_waitcnt vmcnt(24)
	ds_write2_b32 v12, v24, v25 offset0:140 offset1:206
	v_add_u32_e32 v12, 0x800, v5
	s_waitcnt vmcnt(22)
	ds_write2_b32 v12, v26, v27 offset0:16 offset1:82
	s_waitcnt vmcnt(20)
	ds_write2_b32 v12, v30, v31 offset0:148 offset1:214
	v_add_u32_e32 v12, 0xc00, v5
	s_waitcnt vmcnt(18)
	ds_write2_b32 v12, v28, v29 offset0:24 offset1:90
	s_waitcnt vmcnt(16)
	ds_write2_b32 v12, v32, v33 offset0:156 offset1:222
	v_add_u32_e32 v12, 0x1000, v5
	s_waitcnt vmcnt(14)
	ds_write2_b32 v12, v34, v35 offset0:32 offset1:98
	s_waitcnt vmcnt(12)
	ds_write2_b32 v12, v38, v39 offset0:164 offset1:230
	v_add_u32_e32 v12, 0x1400, v5
	s_waitcnt vmcnt(10)
	ds_write2_b32 v12, v36, v37 offset0:40 offset1:106
	s_waitcnt vmcnt(8)
	ds_write2_b32 v12, v40, v41 offset0:172 offset1:238
	v_add_u32_e32 v12, 0x1800, v5
	s_waitcnt vmcnt(6)
	ds_write2_b32 v12, v42, v43 offset0:48 offset1:114
	s_waitcnt vmcnt(4)
	ds_write2_b32 v12, v48, v49 offset0:180 offset1:246
	v_add_u32_e32 v12, 0x1c00, v5
	v_lshlrev_b64 v[20:21], 25, v[20:21]
	s_waitcnt vmcnt(2)
	ds_write2_b32 v12, v46, v47 offset0:56 offset1:122
	s_waitcnt vmcnt(0)
	ds_write2_b32 v12, v44, v45 offset0:188 offset1:254
	v_lshl_add_u64 v[20:21], s[62:63], 0, v[20:21]
	s_waitcnt lgkmcnt(0)
	v_lshlrev_b32_e32 v12, 1, v51
	v_lshl_add_u64 v[16:17], v[20:21], 0, v[12:13]
	ds_read2_b32 v[20:21], v11 offset0:33 offset1:41
	ds_read2_b32 v[22:23], v11 offset1:8
	ds_read2_b32 v[24:25], v11 offset0:66 offset1:74
	ds_read2_b32 v[26:27], v11 offset0:99 offset1:107
	ds_read2_b32 v[28:29], v11 offset0:132 offset1:140
	ds_read2_b32 v[30:31], v11 offset0:165 offset1:173
	ds_read2_b32 v[32:33], v11 offset0:198 offset1:206
	ds_read2_b32 v[34:35], v11 offset0:231 offset1:239
	v_lshlrev_b32_e32 v12, 1, v14
	v_lshl_add_u64 v[36:37], v[16:17], 0, v[12:13]
	v_or_b32_e32 v12, v50, v7
	v_lshlrev_b32_e32 v12, 12, v12
	s_waitcnt lgkmcnt(6)
	v_cvt_pk_bf16_f32 v16, v22, v20
	s_waitcnt lgkmcnt(4)
	v_cvt_pk_bf16_f32 v17, v24, v26
	s_waitcnt lgkmcnt(2)
	v_cvt_pk_bf16_f32 v18, v28, v30
	s_waitcnt lgkmcnt(0)
	v_cvt_pk_bf16_f32 v19, v32, v34
	v_lshl_add_u64 v[38:39], v[36:37], 0, v[12:13]
	global_store_dwordx4 v[38:39], v[16:19], off nt
	v_or_b32_e32 v12, v50, v15
	v_lshlrev_b32_e32 v12, 12, v12
	v_cvt_pk_bf16_f32 v16, v23, v21
	v_cvt_pk_bf16_f32 v17, v25, v27
	v_cvt_pk_bf16_f32 v18, v29, v31
	v_cvt_pk_bf16_f32 v19, v33, v35
	ds_read2_b32 v[22:23], v11 offset0:49 offset1:57
	ds_read2_b32 v[24:25], v11 offset0:16 offset1:24
	ds_read2_b32 v[26:27], v11 offset0:82 offset1:90
	ds_read2_b32 v[28:29], v11 offset0:115 offset1:123
	ds_read2_b32 v[30:31], v11 offset0:148 offset1:156
	ds_read2_b32 v[32:33], v11 offset0:181 offset1:189
	ds_read2_b32 v[34:35], v11 offset0:214 offset1:222
	ds_read2_b32 v[38:39], v11 offset0:247 offset1:255
	v_lshl_add_u64 v[20:21], v[36:37], 0, v[12:13]
	v_or_b32_e32 v12, v50, v56
	v_lshlrev_b32_e32 v12, 12, v12
	global_store_dwordx4 v[20:21], v[16:19], off nt
	v_lshl_add_u64 v[20:21], v[36:37], 0, v[12:13]
	v_or_b32_e32 v12, v50, v57
	s_waitcnt lgkmcnt(6)
	v_cvt_pk_bf16_f32 v16, v24, v22
	s_waitcnt lgkmcnt(4)
	v_cvt_pk_bf16_f32 v17, v26, v28
	s_waitcnt lgkmcnt(2)
	v_cvt_pk_bf16_f32 v18, v30, v32
	s_waitcnt lgkmcnt(0)
	v_cvt_pk_bf16_f32 v19, v34, v38
	v_lshlrev_b32_e32 v12, 12, v12
	global_store_dwordx4 v[20:21], v[16:19], off nt
	v_lshl_add_u64 v[20:21], v[36:37], 0, v[12:13]
	s_nop 0
	v_cvt_pk_bf16_f32 v16, v25, v23
	v_cvt_pk_bf16_f32 v17, v27, v29
	v_cvt_pk_bf16_f32 v18, v31, v33
	v_cvt_pk_bf16_f32 v19, v35, v39
	global_store_dwordx4 v[20:21], v[16:19], off nt
	s_waitcnt lgkmcnt(0)

; __device__ __forceinline__ void transpose_item(const float* W, int ldw, const float* kgain, float scale, bf16_t* WT, int ldt, int k0, int n_src0, int n_dst0, LAS float* scr, int lane) {
;     float wv[32];
; #pragma unroll
;     for (int i = 0; i < 32; ++i) wv[i] = W[(size_t)(k0 + 2 * i + (lane >> 5)) * ldw + n_src0 + (lane & 31)];
; __device__ __forceinline__ void phase_prologue(const P& p, unsigned char* ws, LAS unsigned char* lds, int wg, int nwg) {
;     ...
;         if (r < I_OUT) { transpose_item(p.w_out + (size_t)l * D * D, D, nullptr, 1.f, (bf16_t*)(ws + WS_WOUT) + (size_t)l * D * D, D, (r / (D / 32)) * 64, (r % (D / 32)) * 32, (r % (D / 32)) * 32, scr, lane); continue; } r -= I_OUT;
.LBB0_31:
	s_andn2_saveexec_b64 s[44:45], s[86:87]
	s_cbranch_execz .LBB0_33
	v_ashrrev_i32_e32 v21, 31, v20
	v_lshlrev_b64 v[16:17], 24, v[20:21]
	v_lshl_add_u64 v[18:19], s[40:41], 0, v[16:17]
	v_and_b32_e32 v16, 0x3fc0, v12
	v_lshlrev_b32_e32 v12, 5, v12
	v_and_b32_e32 v40, 0x7e0, v12
	v_add_u32_e32 v16, 0xffffca00, v16
	v_lshlrev_b32_e32 v12, 2, v40
	v_or_b32_e32 v22, v16, v8
	v_lshl_add_u64 v[18:19], v[18:19], 0, v[12:13]
	v_lshlrev_b32_e32 v12, 2, v10
	v_lshl_add_u64 v[18:19], v[18:19], 0, v[12:13]
	v_or_b32_e32 v12, 2, v22
	v_lshlrev_b64 v[26:27], 13, v[12:13]
	v_or_b32_e32 v12, 4, v22
	v_lshlrev_b64 v[28:29], 13, v[12:13]
	v_or_b32_e32 v12, 6, v22
	v_lshlrev_b64 v[30:31], 13, v[12:13]
	v_or_b32_e32 v12, 8, v22
	v_lshlrev_b64 v[32:33], 13, v[12:13]
	v_or_b32_e32 v12, 10, v22
	v_mov_b32_e32 v23, v13
	v_lshlrev_b64 v[34:35], 13, v[12:13]
	v_or_b32_e32 v12, 12, v22
	v_lshlrev_b64 v[24:25], 13, v[22:23]
	v_lshlrev_b64 v[36:37], 13, v[12:13]
	v_or_b32_e32 v12, 14, v22
	v_lshl_add_u64 v[24:25], v[18:19], 0, v[24:25]
	v_lshlrev_b64 v[38:39], 13, v[12:13]
	v_or_b32_e32 v12, 16, v22
	v_lshl_add_u64 v[26:27], v[18:19], 0, v[26:27]
	v_lshl_add_u64 v[28:29], v[18:19], 0, v[28:29]
	v_lshl_add_u64 v[30:31], v[18:19], 0, v[30:31]
	v_lshl_add_u64 v[32:33], v[18:19], 0, v[32:33]
	v_lshl_add_u64 v[34:35], v[18:19], 0, v[34:35]
	v_lshl_add_u64 v[36:37], v[18:19], 0, v[36:37]
	v_lshl_add_u64 v[38:39], v[18:19], 0, v[38:39]
	global_load_dword v17, v[24:25], off
	global_load_dword v41, v[26:27], off
	global_load_dword v42, v[28:29], off
	global_load_dword v43, v[30:31], off
	global_load_dword v44, v[32:33], off
	global_load_dword v45, v[34:35], off
	global_load_dword v46, v[36:37], off
	global_load_dword v47, v[38:39], off
	v_lshlrev_b64 v[24:25], 13, v[12:13]
	v_or_b32_e32 v12, 18, v22
	v_lshlrev_b64 v[26:27], 13, v[12:13]
	v_or_b32_e32 v12, 20, v22
	v_lshlrev_b64 v[28:29], 13, v[12:13]
	v_or_b32_e32 v12, 22, v22
	v_lshlrev_b64 v[30:31], 13, v[12:13]
	v_or_b32_e32 v12, 24, v22
	v_lshlrev_b64 v[32:33], 13, v[12:13]
	v_or_b32_e32 v12, 26, v22
	v_lshlrev_b64 v[34:35], 13, v[12:13]
	v_or_b32_e32 v12, 28, v22
	v_lshlrev_b64 v[36:37], 13, v[12:13]
	v_or_b32_e32 v12, 30, v22
	v_lshl_add_u64 v[24:25], v[18:19], 0, v[24:25]
	v_lshlrev_b64 v[38:39], 13, v[12:13]
	v_or_b32_e32 v12, 32, v22
	v_lshl_add_u64 v[26:27], v[18:19], 0, v[26:27]
	v_lshl_add_u64 v[28:29], v[18:19], 0, v[28:29]
	v_lshl_add_u64 v[30:31], v[18:19], 0, v[30:31]
	v_lshl_add_u64 v[32:33], v[18:19], 0, v[32:33]
	v_lshl_add_u64 v[34:35], v[18:19], 0, v[34:35]
	v_lshl_add_u64 v[36:37], v[18:19], 0, v[36:37]
	v_lshl_add_u64 v[38:39], v[18:19], 0, v[38:39]
	global_load_dword v48, v[24:25], off
	global_load_dword v49, v[26:27], off
	global_load_dword v50, v[28:29], off
	global_load_dword v51, v[30:31], off
	global_load_dword v52, v[32:33], off
	global_load_dword v53, v[34:35], off
	global_load_dword v54, v[36:37], off
	global_load_dword v55, v[38:39], off
	v_lshlrev_b64 v[24:25], 13, v[12:13]
	v_or_b32_e32 v12, 34, v22
	v_lshlrev_b64 v[26:27], 13, v[12:13]
	v_or_b32_e32 v12, 36, v22
	v_lshlrev_b64 v[28:29], 13, v[12:13]
	v_or_b32_e32 v12, 38, v22
	v_lshlrev_b64 v[30:31], 13, v[12:13]
	v_or_b32_e32 v12, 40, v22
	v_lshlrev_b64 v[32:33], 13, v[12:13]
	v_or_b32_e32 v12, 42, v22
	v_lshlrev_b64 v[34:35], 13, v[12:13]
	v_or_b32_e32 v12, 44, v22
	v_lshlrev_b64 v[36:37], 13, v[12:13]
	v_or_b32_e32 v12, 46, v22
	v_lshlrev_b64 v[38:39], 13, v[12:13]
	v_lshl_add_u64 v[24:25], v[18:19], 0, v[24:25]
	v_lshl_add_u64 v[38:39], v[18:19], 0, v[38:39]
	v_or_b32_e32 v12, 48, v22
	v_lshl_add_u64 v[26:27], v[18:19], 0, v[26:27]
	v_lshl_add_u64 v[28:29], v[18:19], 0, v[28:29]
	v_lshl_add_u64 v[30:31], v[18:19], 0, v[30:31]
	v_lshl_add_u64 v[32:33], v[18:19], 0, v[32:33]
	v_lshl_add_u64 v[34:35], v[18:19], 0, v[34:35]
	v_lshl_add_u64 v[36:37], v[18:19], 0, v[36:37]
	global_load_dword v69, v[24:25], off
	global_load_dword v70, v[26:27], off
	global_load_dword v71, v[28:29], off
	global_load_dword v72, v[30:31], off
	global_load_dword v73, v[32:33], off
	global_load_dword v74, v[34:35], off
	global_load_dword v75, v[36:37], off
	s_nop 0
	global_load_dword v38, v[38:39], off
	v_lshlrev_b64 v[24:25], 13, v[12:13]
	v_or_b32_e32 v12, 50, v22
	v_lshlrev_b64 v[26:27], 13, v[12:13]
	v_or_b32_e32 v12, 52, v22
	v_lshlrev_b64 v[28:29], 13, v[12:13]
	v_or_b32_e32 v12, 54, v22
	v_lshlrev_b64 v[30:31], 13, v[12:13]
	v_or_b32_e32 v12, 56, v22
	v_lshlrev_b64 v[32:33], 13, v[12:13]
	v_or_b32_e32 v12, 58, v22
	v_lshlrev_b64 v[34:35], 13, v[12:13]
	v_or_b32_e32 v12, 60, v22
	v_lshlrev_b64 v[36:37], 13, v[12:13]
	v_or_b32_e32 v12, 62, v22
	v_lshl_add_u64 v[24:25], v[18:19], 0, v[24:25]
	v_lshl_add_u64 v[26:27], v[18:19], 0, v[26:27]
	v_lshl_add_u64 v[28:29], v[18:19], 0, v[28:29]
	v_lshlrev_b64 v[22:23], 13, v[12:13]
	v_lshl_add_u64 v[30:31], v[18:19], 0, v[30:31]
	v_lshl_add_u64 v[32:33], v[18:19], 0, v[32:33]
	v_lshl_add_u64 v[34:35], v[18:19], 0, v[34:35]
	v_lshl_add_u64 v[36:37], v[18:19], 0, v[36:37]
	v_lshl_add_u64 v[18:19], v[18:19], 0, v[22:23]
	global_load_dword v12, v[24:25], off
	global_load_dword v22, v[26:27], off
	global_load_dword v23, v[28:29], off
	s_nop 0
	global_load_dword v24, v[30:31], off
	global_load_dword v25, v[32:33], off
	global_load_dword v26, v[34:35], off
	global_load_dword v27, v[36:37], off
	global_load_dword v28, v[18:19], off
	s_waitcnt vmcnt(30)
; #define LAS __attribute__((address_space(3)))
; __device__ __forceinline__ unsigned pk2(float lo, float hi) { return pg8::cvt_pk_bf16(lo, hi); }
; __device__ __forceinline__ void transpose_item(const float* W, int ldw, const float* kgain, float scale, bf16_t* WT, int ldt, int k0, int n_src0, int n_dst0, LAS float* scr, int lane) {
;     ...
;     for (int i = 0; i < 32; ++i) scr[(2 * i + (lane >> 5)) * 33 + (lane & 31)] = wv[i];
;     asm volatile("s_waitcnt lgkmcnt(0)" ::: "memory");
;     const int c = lane & 7;
; #pragma unroll
;     for (int j = 0; j < 4; ++j) { const int n = (lane >> 3) + 8 * j; const LAS float* s = scr + (8 * c) * 33 + n;
;         u32x4 o; o.x = pk2(s[0 * 33], s[1 * 33]); o.y = pk2(s[2 * 33], s[3 * 33]); o.z = pk2(s[4 * 33], s[5 * 33]); o.w = pk2(s[6 * 33], s[7 * 33]);
;         *(u32x4*)(WT + (size_t)(n_dst0 + n) * ldt + k0 + 8 * c) = o; }
;     asm volatile("s_waitcnt lgkmcnt(0)" ::: "memory");
	ds_write2_b32 v5, v17, v41 offset1:66
	s_waitcnt vmcnt(28)
	ds_write2_b32 v5, v42, v43 offset0:132 offset1:198
	v_add_u32_e32 v17, 0x400, v5
	s_waitcnt vmcnt(26)
	ds_write2_b32 v17, v44, v45 offset0:8 offset1:74
	s_waitcnt vmcnt(24)
	ds_write2_b32 v17, v46, v47 offset0:140 offset1:206
	v_add_u32_e32 v17, 0x800, v5
	s_waitcnt vmcnt(22)
	ds_write2_b32 v17, v48, v49 offset0:16 offset1:82
	s_waitcnt vmcnt(20)
	ds_write2_b32 v17, v50, v51 offset0:148 offset1:214
	v_add_u32_e32 v17, 0xc00, v5
	s_waitcnt vmcnt(18)
	ds_write2_b32 v17, v52, v53 offset0:24 offset1:90
	s_waitcnt vmcnt(16)
	ds_write2_b32 v17, v54, v55 offset0:156 offset1:222
	v_add_u32_e32 v17, 0x1000, v5
	s_waitcnt vmcnt(14)
	ds_write2_b32 v17, v69, v70 offset0:32 offset1:98
	s_waitcnt vmcnt(12)
	ds_write2_b32 v17, v71, v72 offset0:164 offset1:230
	v_add_u32_e32 v17, 0x1400, v5
	s_waitcnt vmcnt(10)
	ds_write2_b32 v17, v73, v74 offset0:40 offset1:106
	s_waitcnt vmcnt(8)
	ds_write2_b32 v17, v75, v38 offset0:172 offset1:238
	v_add_u32_e32 v17, 0x1800, v5
	s_waitcnt vmcnt(6)
	ds_write2_b32 v17, v12, v22 offset0:48 offset1:114
	s_waitcnt vmcnt(4)
	ds_write2_b32 v17, v23, v24 offset0:180 offset1:246
	v_add_u32_e32 v12, 0x1c00, v5
	s_waitcnt vmcnt(2)
	ds_write2_b32 v12, v25, v26 offset0:56 offset1:122
	s_waitcnt vmcnt(0)
	ds_write2_b32 v12, v27, v28 offset0:188 offset1:254
	s_waitcnt lgkmcnt(0)
	v_lshlrev_b64 v[18:19], 23, v[20:21]
	ds_read2_b32 v[20:21], v11 offset0:33 offset1:41
	ds_read2_b32 v[22:23], v11 offset1:8
	ds_read2_b32 v[24:25], v11 offset0:66 offset1:74
	ds_read2_b32 v[26:27], v11 offset0:99 offset1:107
	ds_read2_b32 v[28:29], v11 offset0:132 offset1:140
	ds_read2_b32 v[30:31], v11 offset0:165 offset1:173
	ds_read2_b32 v[32:33], v11 offset0:198 offset1:206
	ds_read2_b32 v[34:35], v11 offset0:231 offset1:239
	v_lshl_add_u64 v[18:19], s[64:65], 0, v[18:19]
	v_mov_b32_e32 v17, v13
	v_lshl_add_u64 v[16:17], v[16:17], 1, v[18:19]
	v_lshlrev_b32_e32 v12, 1, v14
	v_lshl_add_u64 v[36:37], v[16:17], 0, v[12:13]
	v_or_b32_e32 v12, v40, v7
	v_lshlrev_b32_e32 v12, 12, v12
	s_waitcnt lgkmcnt(6)
	v_cvt_pk_bf16_f32 v16, v22, v20
	s_waitcnt lgkmcnt(4)
	v_cvt_pk_bf16_f32 v17, v24, v26
	s_waitcnt lgkmcnt(2)
	v_cvt_pk_bf16_f32 v18, v28, v30
	s_waitcnt lgkmcnt(0)
	v_cvt_pk_bf16_f32 v19, v32, v34
	v_lshl_add_u64 v[38:39], v[36:37], 0, v[12:13]
	global_store_dwordx4 v[38:39], v[16:19], off nt
	v_or_b32_e32 v12, v40, v15
	v_lshlrev_b32_e32 v12, 12, v12
	v_cvt_pk_bf16_f32 v16, v23, v21
	v_cvt_pk_bf16_f32 v17, v25, v27
	v_cvt_pk_bf16_f32 v18, v29, v31
	v_cvt_pk_bf16_f32 v19, v33, v35
	ds_read2_b32 v[22:23], v11 offset0:49 offset1:57
	ds_read2_b32 v[24:25], v11 offset0:16 offset1:24
	ds_read2_b32 v[26:27], v11 offset0:82 offset1:90
	ds_read2_b32 v[28:29], v11 offset0:115 offset1:123
	ds_read2_b32 v[30:31], v11 offset0:148 offset1:156
	ds_read2_b32 v[32:33], v11 offset0:181 offset1:189
	ds_read2_b32 v[34:35], v11 offset0:214 offset1:222
	ds_read2_b32 v[38:39], v11 offset0:247 offset1:255
	v_lshl_add_u64 v[20:21], v[36:37], 0, v[12:13]
	v_or_b32_e32 v12, v40, v56
	v_lshlrev_b32_e32 v12, 12, v12
	global_store_dwordx4 v[20:21], v[16:19], off nt
	v_lshl_add_u64 v[20:21], v[36:37], 0, v[12:13]
	v_or_b32_e32 v12, v40, v57
	s_waitcnt lgkmcnt(6)
	v_cvt_pk_bf16_f32 v16, v24, v22
	s_waitcnt lgkmcnt(4)
	v_cvt_pk_bf16_f32 v17, v26, v28
	s_waitcnt lgkmcnt(2)
	v_cvt_pk_bf16_f32 v18, v30, v32
	s_waitcnt lgkmcnt(0)
	v_cvt_pk_bf16_f32 v19, v34, v38
	v_lshlrev_b32_e32 v12, 12, v12
	global_store_dwordx4 v[20:21], v[16:19], off nt
	v_lshl_add_u64 v[20:21], v[36:37], 0, v[12:13]
	s_nop 0
	v_cvt_pk_bf16_f32 v16, v25, v23
	v_cvt_pk_bf16_f32 v17, v27, v29
	v_cvt_pk_bf16_f32 v18, v31, v33
	v_cvt_pk_bf16_f32 v19, v35, v39
	global_store_dwordx4 v[20:21], v[16:19], off nt
	s_waitcnt lgkmcnt(0)

; __device__ __forceinline__ void transpose_item(const float* W, int ldw, const float* kgain, float scale, bf16_t* WT, int ldt, int k0, int n_src0, int n_dst0, LAS float* scr, int lane) {
;     float wv[32];
; #pragma unroll
;     for (int i = 0; i < 32; ++i) wv[i] = W[(size_t)(k0 + 2 * i + (lane >> 5)) * ldw + n_src0 + (lane & 31)];
; __device__ __forceinline__ void phase_prologue(const P& p, unsigned char* ws, LAS unsigned char* lds, int wg, int nwg) {
;     ...
;         if (r < I_UG) { transpose_item(p.w_gup + (size_t)l * GVW * D, D, nullptr, 1.f, (bf16_t*)(ws + WS_WUG) + (size_t)l * D * GVW, GVW, (r / (D / 32)) * 64, (r % (D / 32)) * 32, (r % (D / 32)) * 32, scr, lane); continue; } r -= I_UG;
.LBB0_34:
	s_andn2_saveexec_b64 s[44:45], s[84:85]
	s_cbranch_execz .LBB0_36
	v_ashrrev_i32_e32 v21, 31, v20
	v_lshlrev_b64 v[16:17], 23, v[20:21]
	v_lshl_add_u64 v[18:19], s[38:39], 0, v[16:17]
	v_and_b32_e32 v16, 0x3fc0, v12
	v_lshlrev_b32_e32 v12, 5, v12
	v_and_b32_e32 v40, 0x7e0, v12
	v_add_u32_e32 v16, 0xffffce00, v16
	v_lshlrev_b32_e32 v12, 2, v40
	v_or_b32_e32 v22, v16, v8
	v_lshl_add_u64 v[18:19], v[18:19], 0, v[12:13]
	v_lshlrev_b32_e32 v12, 2, v10
	v_lshl_add_u64 v[18:19], v[18:19], 0, v[12:13]
	v_or_b32_e32 v12, 2, v22
	v_lshlrev_b64 v[26:27], 13, v[12:13]
	v_or_b32_e32 v12, 4, v22
	v_lshlrev_b64 v[28:29], 13, v[12:13]
	v_or_b32_e32 v12, 6, v22
	v_lshlrev_b64 v[30:31], 13, v[12:13]
	v_or_b32_e32 v12, 8, v22
	v_lshlrev_b64 v[32:33], 13, v[12:13]
	v_or_b32_e32 v12, 10, v22
	v_mov_b32_e32 v23, v13
	v_lshlrev_b64 v[34:35], 13, v[12:13]
	v_or_b32_e32 v12, 12, v22
	v_lshlrev_b64 v[24:25], 13, v[22:23]
	v_lshlrev_b64 v[36:37], 13, v[12:13]
	v_or_b32_e32 v12, 14, v22
	v_lshl_add_u64 v[24:25], v[18:19], 0, v[24:25]
	v_lshlrev_b64 v[38:39], 13, v[12:13]
	v_or_b32_e32 v12, 16, v22
	v_lshl_add_u64 v[26:27], v[18:19], 0, v[26:27]
	v_lshl_add_u64 v[28:29], v[18:19], 0, v[28:29]
	v_lshl_add_u64 v[30:31], v[18:19], 0, v[30:31]
	v_lshl_add_u64 v[32:33], v[18:19], 0, v[32:33]
	v_lshl_add_u64 v[34:35], v[18:19], 0, v[34:35]
	v_lshl_add_u64 v[36:37], v[18:19], 0, v[36:37]
	v_lshl_add_u64 v[38:39], v[18:19], 0, v[38:39]
	global_load_dword v17, v[24:25], off
	global_load_dword v41, v[26:27], off
	global_load_dword v42, v[28:29], off
	global_load_dword v43, v[30:31], off
	global_load_dword v44, v[32:33], off
	global_load_dword v45, v[34:35], off
	global_load_dword v46, v[36:37], off
	global_load_dword v47, v[38:39], off
	v_lshlrev_b64 v[24:25], 13, v[12:13]
	v_or_b32_e32 v12, 18, v22
	v_lshlrev_b64 v[26:27], 13, v[12:13]
	v_or_b32_e32 v12, 20, v22
	v_lshlrev_b64 v[28:29], 13, v[12:13]
	v_or_b32_e32 v12, 22, v22
	v_lshlrev_b64 v[30:31], 13, v[12:13]
	v_or_b32_e32 v12, 24, v22
	v_lshlrev_b64 v[32:33], 13, v[12:13]
	v_or_b32_e32 v12, 26, v22
	v_lshlrev_b64 v[34:35], 13, v[12:13]
	v_or_b32_e32 v12, 28, v22
	v_lshlrev_b64 v[36:37], 13, v[12:13]
	v_or_b32_e32 v12, 30, v22
	v_lshl_add_u64 v[24:25], v[18:19], 0, v[24:25]
	v_lshlrev_b64 v[38:39], 13, v[12:13]
	v_or_b32_e32 v12, 32, v22
	v_lshl_add_u64 v[26:27], v[18:19], 0, v[26:27]
	v_lshl_add_u64 v[28:29], v[18:19], 0, v[28:29]
	v_lshl_add_u64 v[30:31], v[18:19], 0, v[30:31]
	v_lshl_add_u64 v[32:33], v[18:19], 0, v[32:33]
	v_lshl_add_u64 v[34:35], v[18:19], 0, v[34:35]
	v_lshl_add_u64 v[36:37], v[18:19], 0, v[36:37]
	v_lshl_add_u64 v[38:39], v[18:19], 0, v[38:39]
	global_load_dword v48, v[24:25], off
	global_load_dword v49, v[26:27], off
	global_load_dword v50, v[28:29], off
	global_load_dword v51, v[30:31], off
	global_load_dword v52, v[32:33], off
	global_load_dword v53, v[34:35], off
	global_load_dword v54, v[36:37], off
	global_load_dword v55, v[38:39], off
	v_lshlrev_b64 v[24:25], 13, v[12:13]
	v_or_b32_e32 v12, 34, v22
	v_lshlrev_b64 v[26:27], 13, v[12:13]
	v_or_b32_e32 v12, 36, v22
	v_lshlrev_b64 v[28:29], 13, v[12:13]
	v_or_b32_e32 v12, 38, v22
	v_lshlrev_b64 v[30:31], 13, v[12:13]
	v_or_b32_e32 v12, 40, v22
	v_lshlrev_b64 v[32:33], 13, v[12:13]
	v_or_b32_e32 v12, 42, v22
	v_lshlrev_b64 v[34:35], 13, v[12:13]
	v_or_b32_e32 v12, 44, v22
	v_lshlrev_b64 v[36:37], 13, v[12:13]
	v_or_b32_e32 v12, 46, v22
	v_lshlrev_b64 v[38:39], 13, v[12:13]
	v_lshl_add_u64 v[24:25], v[18:19], 0, v[24:25]
	v_lshl_add_u64 v[38:39], v[18:19], 0, v[38:39]
	v_or_b32_e32 v12, 48, v22
	v_lshl_add_u64 v[26:27], v[18:19], 0, v[26:27]
	v_lshl_add_u64 v[28:29], v[18:19], 0, v[28:29]
	v_lshl_add_u64 v[30:31], v[18:19], 0, v[30:31]
	v_lshl_add_u64 v[32:33], v[18:19], 0, v[32:33]
	v_lshl_add_u64 v[34:35], v[18:19], 0, v[34:35]
	v_lshl_add_u64 v[36:37], v[18:19], 0, v[36:37]
	global_load_dword v69, v[24:25], off
	global_load_dword v70, v[26:27], off
	global_load_dword v71, v[28:29], off
	global_load_dword v72, v[30:31], off
	global_load_dword v73, v[32:33], off
	global_load_dword v74, v[34:35], off
	global_load_dword v75, v[36:37], off
	s_nop 0
	global_load_dword v38, v[38:39], off
	v_lshlrev_b64 v[24:25], 13, v[12:13]
	v_or_b32_e32 v12, 50, v22
	v_lshlrev_b64 v[26:27], 13, v[12:13]
	v_or_b32_e32 v12, 52, v22
	v_lshlrev_b64 v[28:29], 13, v[12:13]
	v_or_b32_e32 v12, 54, v22
	v_lshlrev_b64 v[30:31], 13, v[12:13]
	v_or_b32_e32 v12, 56, v22
	v_lshlrev_b64 v[32:33], 13, v[12:13]
	v_or_b32_e32 v12, 58, v22
	v_lshlrev_b64 v[34:35], 13, v[12:13]
	v_or_b32_e32 v12, 60, v22
	v_lshlrev_b64 v[36:37], 13, v[12:13]
	v_or_b32_e32 v12, 62, v22
	v_lshl_add_u64 v[24:25], v[18:19], 0, v[24:25]
	v_lshl_add_u64 v[26:27], v[18:19], 0, v[26:27]
	v_lshl_add_u64 v[28:29], v[18:19], 0, v[28:29]
	v_lshlrev_b64 v[22:23], 13, v[12:13]
	v_lshl_add_u64 v[30:31], v[18:19], 0, v[30:31]
	v_lshl_add_u64 v[32:33], v[18:19], 0, v[32:33]
	v_lshl_add_u64 v[34:35], v[18:19], 0, v[34:35]
	v_lshl_add_u64 v[36:37], v[18:19], 0, v[36:37]
	v_lshl_add_u64 v[18:19], v[18:19], 0, v[22:23]
	global_load_dword v12, v[24:25], off
	global_load_dword v22, v[26:27], off
	global_load_dword v23, v[28:29], off
	s_nop 0
	global_load_dword v24, v[30:31], off
	global_load_dword v25, v[32:33], off
	global_load_dword v26, v[34:35], off
	global_load_dword v27, v[36:37], off
	global_load_dword v28, v[18:19], off
	s_waitcnt vmcnt(30)
; #define LAS __attribute__((address_space(3)))
; __device__ __forceinline__ unsigned pk2(float lo, float hi) { return pg8::cvt_pk_bf16(lo, hi); }
; __device__ __forceinline__ void transpose_item(const float* W, int ldw, const float* kgain, float scale, bf16_t* WT, int ldt, int k0, int n_src0, int n_dst0, LAS float* scr, int lane) {
;     ...
;     for (int i = 0; i < 32; ++i) scr[(2 * i + (lane >> 5)) * 33 + (lane & 31)] = wv[i];
;     asm volatile("s_waitcnt lgkmcnt(0)" ::: "memory");
;     const int c = lane & 7;
; #pragma unroll
;     for (int j = 0; j < 4; ++j) { const int n = (lane >> 3) + 8 * j; const LAS float* s = scr + (8 * c) * 33 + n;
;         u32x4 o; o.x = pk2(s[0 * 33], s[1 * 33]); o.y = pk2(s[2 * 33], s[3 * 33]); o.z = pk2(s[4 * 33], s[5 * 33]); o.w = pk2(s[6 * 33], s[7 * 33]);
;         *(u32x4*)(WT + (size_t)(n_dst0 + n) * ldt + k0 + 8 * c) = o; }
;     asm volatile("s_waitcnt lgkmcnt(0)" ::: "memory");
	ds_write2_b32 v5, v17, v41 offset1:66
	s_waitcnt vmcnt(28)
	ds_write2_b32 v5, v42, v43 offset0:132 offset1:198
	v_add_u32_e32 v17, 0x400, v5
	s_waitcnt vmcnt(26)
	ds_write2_b32 v17, v44, v45 offset0:8 offset1:74
	s_waitcnt vmcnt(24)
	ds_write2_b32 v17, v46, v47 offset0:140 offset1:206
	v_add_u32_e32 v17, 0x800, v5
	s_waitcnt vmcnt(22)
	ds_write2_b32 v17, v48, v49 offset0:16 offset1:82
	s_waitcnt vmcnt(20)
	ds_write2_b32 v17, v50, v51 offset0:148 offset1:214
	v_add_u32_e32 v17, 0xc00, v5
	s_waitcnt vmcnt(18)
	ds_write2_b32 v17, v52, v53 offset0:24 offset1:90
	s_waitcnt vmcnt(16)
	ds_write2_b32 v17, v54, v55 offset0:156 offset1:222
	v_add_u32_e32 v17, 0x1000, v5
	s_waitcnt vmcnt(14)
	ds_write2_b32 v17, v69, v70 offset0:32 offset1:98
	s_waitcnt vmcnt(12)
	ds_write2_b32 v17, v71, v72 offset0:164 offset1:230
	v_add_u32_e32 v17, 0x1400, v5
	s_waitcnt vmcnt(10)
	ds_write2_b32 v17, v73, v74 offset0:40 offset1:106
	s_waitcnt vmcnt(8)
	ds_write2_b32 v17, v75, v38 offset0:172 offset1:238
	v_add_u32_e32 v17, 0x1800, v5
	s_waitcnt vmcnt(6)
	ds_write2_b32 v17, v12, v22 offset0:48 offset1:114
	s_waitcnt vmcnt(4)
	ds_write2_b32 v17, v23, v24 offset0:180 offset1:246
	v_add_u32_e32 v12, 0x1c00, v5
	s_waitcnt vmcnt(2)
	ds_write2_b32 v12, v25, v26 offset0:56 offset1:122
	s_waitcnt vmcnt(0)
	ds_write2_b32 v12, v27, v28 offset0:188 offset1:254
	s_waitcnt lgkmcnt(0)
	v_lshlrev_b64 v[18:19], 22, v[20:21]
	ds_read2_b32 v[20:21], v11 offset0:33 offset1:41
	ds_read2_b32 v[22:23], v11 offset1:8
	ds_read2_b32 v[24:25], v11 offset0:66 offset1:74
	ds_read2_b32 v[26:27], v11 offset0:99 offset1:107
	ds_read2_b32 v[28:29], v11 offset0:132 offset1:140
	ds_read2_b32 v[30:31], v11 offset0:165 offset1:173
	ds_read2_b32 v[32:33], v11 offset0:198 offset1:206
	ds_read2_b32 v[34:35], v11 offset0:231 offset1:239
	v_lshl_add_u64 v[18:19], s[66:67], 0, v[18:19]
	v_mov_b32_e32 v17, v13
	v_lshl_add_u64 v[16:17], v[16:17], 1, v[18:19]
	v_lshlrev_b32_e32 v12, 1, v14
	v_lshl_add_u64 v[36:37], v[16:17], 0, v[12:13]
	v_or_b32_e32 v12, v40, v7
	v_lshlrev_b32_e32 v12, 11, v12
	s_waitcnt lgkmcnt(6)
	v_cvt_pk_bf16_f32 v16, v22, v20
	s_waitcnt lgkmcnt(4)
	v_cvt_pk_bf16_f32 v17, v24, v26
	s_waitcnt lgkmcnt(2)
	v_cvt_pk_bf16_f32 v18, v28, v30
	s_waitcnt lgkmcnt(0)
	v_cvt_pk_bf16_f32 v19, v32, v34
	v_lshl_add_u64 v[38:39], v[36:37], 0, v[12:13]
	global_store_dwordx4 v[38:39], v[16:19], off nt
	v_or_b32_e32 v12, v40, v15
	v_lshlrev_b32_e32 v12, 11, v12
	v_cvt_pk_bf16_f32 v16, v23, v21
	v_cvt_pk_bf16_f32 v17, v25, v27
	v_cvt_pk_bf16_f32 v18, v29, v31
	v_cvt_pk_bf16_f32 v19, v33, v35
	ds_read2_b32 v[22:23], v11 offset0:49 offset1:57
	ds_read2_b32 v[24:25], v11 offset0:16 offset1:24
	ds_read2_b32 v[26:27], v11 offset0:82 offset1:90
	ds_read2_b32 v[28:29], v11 offset0:115 offset1:123
	ds_read2_b32 v[30:31], v11 offset0:148 offset1:156
	ds_read2_b32 v[32:33], v11 offset0:181 offset1:189
	ds_read2_b32 v[34:35], v11 offset0:214 offset1:222
	ds_read2_b32 v[38:39], v11 offset0:247 offset1:255
	v_lshl_add_u64 v[20:21], v[36:37], 0, v[12:13]
	v_or_b32_e32 v12, v40, v56
	v_lshlrev_b32_e32 v12, 11, v12
	global_store_dwordx4 v[20:21], v[16:19], off nt
	v_lshl_add_u64 v[20:21], v[36:37], 0, v[12:13]
	v_or_b32_e32 v12, v40, v57
	s_waitcnt lgkmcnt(6)
	v_cvt_pk_bf16_f32 v16, v24, v22
	s_waitcnt lgkmcnt(4)
	v_cvt_pk_bf16_f32 v17, v26, v28
	s_waitcnt lgkmcnt(2)
	v_cvt_pk_bf16_f32 v18, v30, v32
	s_waitcnt lgkmcnt(0)
	v_cvt_pk_bf16_f32 v19, v34, v38
	v_lshlrev_b32_e32 v12, 11, v12
	global_store_dwordx4 v[20:21], v[16:19], off nt
	v_lshl_add_u64 v[20:21], v[36:37], 0, v[12:13]
	s_nop 0
	v_cvt_pk_bf16_f32 v16, v25, v23
	v_cvt_pk_bf16_f32 v17, v27, v29
	v_cvt_pk_bf16_f32 v18, v31, v33
	v_cvt_pk_bf16_f32 v19, v35, v39
	global_store_dwordx4 v[20:21], v[16:19], off nt
	s_waitcnt lgkmcnt(0)

; __device__ __forceinline__ void transpose_item(const float* W, int ldw, const float* kgain, float scale, bf16_t* WT, int ldt, int k0, int n_src0, int n_dst0, LAS float* scr, int lane) {
;     float wv[32];
; #pragma unroll
;     for (int i = 0; i < 32; ++i) wv[i] = W[(size_t)(k0 + 2 * i + (lane >> 5)) * ldw + n_src0 + (lane & 31)];
; __device__ __forceinline__ void phase_prologue(const P& p, unsigned char* ws, LAS unsigned char* lds, int wg, int nwg) {
;     ...
;         if (r < I_UH) { transpose_item(p.w_hup + (size_t)l * HW * D, D, nullptr, 1.f, (bf16_t*)(ws + WS_WUH) + (size_t)l * D * HW, HW, (r / (D / 32)) * 64, (r % (D / 32)) * 32, (r % (D / 32)) * 32, scr, lane); continue; } r -= I_UH;
.LBB0_37:
	s_andn2_saveexec_b64 s[44:45], s[82:83]
	s_cbranch_execz .LBB0_39
	v_ashrrev_i32_e32 v21, 31, v20
	v_lshlrev_b64 v[16:17], 23, v[20:21]
	v_lshl_add_u64 v[18:19], s[34:35], 0, v[16:17]
	v_and_b32_e32 v16, 0x3fc0, v12
	v_lshlrev_b32_e32 v12, 5, v12
	v_and_b32_e32 v40, 0x7e0, v12
	v_add_u32_e32 v16, 0xffffd200, v16
	v_lshlrev_b32_e32 v12, 2, v40
	v_or_b32_e32 v22, v16, v8
	v_lshl_add_u64 v[18:19], v[18:19], 0, v[12:13]
	v_lshlrev_b32_e32 v12, 2, v10
	v_lshl_add_u64 v[18:19], v[18:19], 0, v[12:13]
	v_or_b32_e32 v12, 2, v22
	v_lshlrev_b64 v[26:27], 13, v[12:13]
	v_or_b32_e32 v12, 4, v22
	v_lshlrev_b64 v[28:29], 13, v[12:13]
	v_or_b32_e32 v12, 6, v22
	v_lshlrev_b64 v[30:31], 13, v[12:13]
	v_or_b32_e32 v12, 8, v22
	v_lshlrev_b64 v[32:33], 13, v[12:13]
	v_or_b32_e32 v12, 10, v22
	v_mov_b32_e32 v23, v13
	v_lshlrev_b64 v[34:35], 13, v[12:13]
	v_or_b32_e32 v12, 12, v22
	v_lshlrev_b64 v[24:25], 13, v[22:23]
	v_lshlrev_b64 v[36:37], 13, v[12:13]
	v_or_b32_e32 v12, 14, v22
	v_lshl_add_u64 v[24:25], v[18:19], 0, v[24:25]
	v_lshlrev_b64 v[38:39], 13, v[12:13]
	v_or_b32_e32 v12, 16, v22
	v_lshl_add_u64 v[26:27], v[18:19], 0, v[26:27]
	v_lshl_add_u64 v[28:29], v[18:19], 0, v[28:29]
	v_lshl_add_u64 v[30:31], v[18:19], 0, v[30:31]
	v_lshl_add_u64 v[32:33], v[18:19], 0, v[32:33]
	v_lshl_add_u64 v[34:35], v[18:19], 0, v[34:35]
	v_lshl_add_u64 v[36:37], v[18:19], 0, v[36:37]
	v_lshl_add_u64 v[38:39], v[18:19], 0, v[38:39]
	global_load_dword v17, v[24:25], off
	global_load_dword v41, v[26:27], off
	global_load_dword v42, v[28:29], off
	global_load_dword v43, v[30:31], off
	global_load_dword v44, v[32:33], off
	global_load_dword v45, v[34:35], off
	global_load_dword v46, v[36:37], off
	global_load_dword v47, v[38:39], off
	v_lshlrev_b64 v[24:25], 13, v[12:13]
	v_or_b32_e32 v12, 18, v22
	v_lshlrev_b64 v[26:27], 13, v[12:13]
	v_or_b32_e32 v12, 20, v22
	v_lshlrev_b64 v[28:29], 13, v[12:13]
	v_or_b32_e32 v12, 22, v22
	v_lshlrev_b64 v[30:31], 13, v[12:13]
	v_or_b32_e32 v12, 24, v22
	v_lshlrev_b64 v[32:33], 13, v[12:13]
	v_or_b32_e32 v12, 26, v22
	v_lshlrev_b64 v[34:35], 13, v[12:13]
	v_or_b32_e32 v12, 28, v22
	v_lshlrev_b64 v[36:37], 13, v[12:13]
	v_or_b32_e32 v12, 30, v22
	v_lshl_add_u64 v[24:25], v[18:19], 0, v[24:25]
	v_lshlrev_b64 v[38:39], 13, v[12:13]
	v_or_b32_e32 v12, 32, v22
	v_lshl_add_u64 v[26:27], v[18:19], 0, v[26:27]
	v_lshl_add_u64 v[28:29], v[18:19], 0, v[28:29]
	v_lshl_add_u64 v[30:31], v[18:19], 0, v[30:31]
	v_lshl_add_u64 v[32:33], v[18:19], 0, v[32:33]
	v_lshl_add_u64 v[34:35], v[18:19], 0, v[34:35]
	v_lshl_add_u64 v[36:37], v[18:19], 0, v[36:37]
	v_lshl_add_u64 v[38:39], v[18:19], 0, v[38:39]
	global_load_dword v48, v[24:25], off
	global_load_dword v49, v[26:27], off
	global_load_dword v50, v[28:29], off
	global_load_dword v51, v[30:31], off
	global_load_dword v52, v[32:33], off
	global_load_dword v53, v[34:35], off
	global_load_dword v54, v[36:37], off
	global_load_dword v55, v[38:39], off
	v_lshlrev_b64 v[24:25], 13, v[12:13]
	v_or_b32_e32 v12, 34, v22
	v_lshlrev_b64 v[26:27], 13, v[12:13]
	v_or_b32_e32 v12, 36, v22
	v_lshlrev_b64 v[28:29], 13, v[12:13]
	v_or_b32_e32 v12, 38, v22
	v_lshlrev_b64 v[30:31], 13, v[12:13]
	v_or_b32_e32 v12, 40, v22
	v_lshlrev_b64 v[32:33], 13, v[12:13]
	v_or_b32_e32 v12, 42, v22
	v_lshlrev_b64 v[34:35], 13, v[12:13]
	v_or_b32_e32 v12, 44, v22
	v_lshlrev_b64 v[36:37], 13, v[12:13]
	v_or_b32_e32 v12, 46, v22
	v_lshlrev_b64 v[38:39], 13, v[12:13]
	v_lshl_add_u64 v[24:25], v[18:19], 0, v[24:25]
	v_lshl_add_u64 v[38:39], v[18:19], 0, v[38:39]
	v_or_b32_e32 v12, 48, v22
	v_lshl_add_u64 v[26:27], v[18:19], 0, v[26:27]
	v_lshl_add_u64 v[28:29], v[18:19], 0, v[28:29]
	v_lshl_add_u64 v[30:31], v[18:19], 0, v[30:31]
	v_lshl_add_u64 v[32:33], v[18:19], 0, v[32:33]
	v_lshl_add_u64 v[34:35], v[18:19], 0, v[34:35]
	v_lshl_add_u64 v[36:37], v[18:19], 0, v[36:37]
	global_load_dword v69, v[24:25], off
	global_load_dword v70, v[26:27], off
	global_load_dword v71, v[28:29], off
	global_load_dword v72, v[30:31], off
	global_load_dword v73, v[32:33], off
	global_load_dword v74, v[34:35], off
	global_load_dword v75, v[36:37], off
	s_nop 0
	global_load_dword v38, v[38:39], off
	v_lshlrev_b64 v[24:25], 13, v[12:13]
	v_or_b32_e32 v12, 50, v22
	v_lshlrev_b64 v[26:27], 13, v[12:13]
	v_or_b32_e32 v12, 52, v22
	v_lshlrev_b64 v[28:29], 13, v[12:13]
	v_or_b32_e32 v12, 54, v22
	v_lshlrev_b64 v[30:31], 13, v[12:13]
	v_or_b32_e32 v12, 56, v22
	v_lshlrev_b64 v[32:33], 13, v[12:13]
	v_or_b32_e32 v12, 58, v22
	v_lshlrev_b64 v[34:35], 13, v[12:13]
	v_or_b32_e32 v12, 60, v22
	v_lshlrev_b64 v[36:37], 13, v[12:13]
	v_or_b32_e32 v12, 62, v22
	v_lshl_add_u64 v[24:25], v[18:19], 0, v[24:25]
	v_lshl_add_u64 v[26:27], v[18:19], 0, v[26:27]
	v_lshl_add_u64 v[28:29], v[18:19], 0, v[28:29]
	v_lshlrev_b64 v[22:23], 13, v[12:13]
	v_lshl_add_u64 v[30:31], v[18:19], 0, v[30:31]
	v_lshl_add_u64 v[32:33], v[18:19], 0, v[32:33]
	v_lshl_add_u64 v[34:35], v[18:19], 0, v[34:35]
	v_lshl_add_u64 v[36:37], v[18:19], 0, v[36:37]
	v_lshl_add_u64 v[18:19], v[18:19], 0, v[22:23]
	global_load_dword v12, v[24:25], off
	global_load_dword v22, v[26:27], off
	global_load_dword v23, v[28:29], off
	s_nop 0
	global_load_dword v24, v[30:31], off
	global_load_dword v25, v[32:33], off
	global_load_dword v26, v[34:35], off
	global_load_dword v27, v[36:37], off
	global_load_dword v28, v[18:19], off
	s_waitcnt vmcnt(30)
; #define LAS __attribute__((address_space(3)))
; __device__ __forceinline__ unsigned pk2(float lo, float hi) { return pg8::cvt_pk_bf16(lo, hi); }
; __device__ __forceinline__ void transpose_item(const float* W, int ldw, const float* kgain, float scale, bf16_t* WT, int ldt, int k0, int n_src0, int n_dst0, LAS float* scr, int lane) {
;     ...
;     for (int i = 0; i < 32; ++i) scr[(2 * i + (lane >> 5)) * 33 + (lane & 31)] = wv[i];
;     asm volatile("s_waitcnt lgkmcnt(0)" ::: "memory");
;     const int c = lane & 7;
; #pragma unroll
;     for (int j = 0; j < 4; ++j) { const int n = (lane >> 3) + 8 * j; const LAS float* s = scr + (8 * c) * 33 + n;
;         u32x4 o; o.x = pk2(s[0 * 33], s[1 * 33]); o.y = pk2(s[2 * 33], s[3 * 33]); o.z = pk2(s[4 * 33], s[5 * 33]); o.w = pk2(s[6 * 33], s[7 * 33]);
;         *(u32x4*)(WT + (size_t)(n_dst0 + n) * ldt + k0 + 8 * c) = o; }
;     asm volatile("s_waitcnt lgkmcnt(0)" ::: "memory");
	ds_write2_b32 v5, v17, v41 offset1:66
	s_waitcnt vmcnt(28)
	ds_write2_b32 v5, v42, v43 offset0:132 offset1:198
	v_add_u32_e32 v17, 0x400, v5
	s_waitcnt vmcnt(26)
	ds_write2_b32 v17, v44, v45 offset0:8 offset1:74
	s_waitcnt vmcnt(24)
	ds_write2_b32 v17, v46, v47 offset0:140 offset1:206
	v_add_u32_e32 v17, 0x800, v5
	s_waitcnt vmcnt(22)
	ds_write2_b32 v17, v48, v49 offset0:16 offset1:82
	s_waitcnt vmcnt(20)
	ds_write2_b32 v17, v50, v51 offset0:148 offset1:214
	v_add_u32_e32 v17, 0xc00, v5
	s_waitcnt vmcnt(18)
	ds_write2_b32 v17, v52, v53 offset0:24 offset1:90
	s_waitcnt vmcnt(16)
	ds_write2_b32 v17, v54, v55 offset0:156 offset1:222
	v_add_u32_e32 v17, 0x1000, v5
	s_waitcnt vmcnt(14)
	ds_write2_b32 v17, v69, v70 offset0:32 offset1:98
	s_waitcnt vmcnt(12)
	ds_write2_b32 v17, v71, v72 offset0:164 offset1:230
	v_add_u32_e32 v17, 0x1400, v5
	s_waitcnt vmcnt(10)
	ds_write2_b32 v17, v73, v74 offset0:40 offset1:106
	s_waitcnt vmcnt(8)
	ds_write2_b32 v17, v75, v38 offset0:172 offset1:238
	v_add_u32_e32 v17, 0x1800, v5
	s_waitcnt vmcnt(6)
	ds_write2_b32 v17, v12, v22 offset0:48 offset1:114
	s_waitcnt vmcnt(4)
	ds_write2_b32 v17, v23, v24 offset0:180 offset1:246
	v_add_u32_e32 v12, 0x1c00, v5
	s_waitcnt vmcnt(2)
	ds_write2_b32 v12, v25, v26 offset0:56 offset1:122
	s_waitcnt vmcnt(0)
	ds_write2_b32 v12, v27, v28 offset0:188 offset1:254
	s_waitcnt lgkmcnt(0)
	v_lshlrev_b64 v[18:19], 22, v[20:21]
	ds_read2_b32 v[20:21], v11 offset0:33 offset1:41
	ds_read2_b32 v[22:23], v11 offset1:8
	ds_read2_b32 v[24:25], v11 offset0:66 offset1:74
	ds_read2_b32 v[26:27], v11 offset0:99 offset1:107
	ds_read2_b32 v[28:29], v11 offset0:132 offset1:140
	ds_read2_b32 v[30:31], v11 offset0:165 offset1:173
	ds_read2_b32 v[32:33], v11 offset0:198 offset1:206
	ds_read2_b32 v[34:35], v11 offset0:231 offset1:239
	v_lshl_add_u64 v[18:19], s[68:69], 0, v[18:19]
	v_mov_b32_e32 v17, v13
	v_lshl_add_u64 v[16:17], v[16:17], 1, v[18:19]
	v_lshlrev_b32_e32 v12, 1, v14
	v_lshl_add_u64 v[36:37], v[16:17], 0, v[12:13]
	v_or_b32_e32 v12, v40, v7
	v_lshlrev_b32_e32 v12, 11, v12
	s_waitcnt lgkmcnt(6)
	v_cvt_pk_bf16_f32 v16, v22, v20
	s_waitcnt lgkmcnt(4)
	v_cvt_pk_bf16_f32 v17, v24, v26
	s_waitcnt lgkmcnt(2)
	v_cvt_pk_bf16_f32 v18, v28, v30
	s_waitcnt lgkmcnt(0)
	v_cvt_pk_bf16_f32 v19, v32, v34
	v_lshl_add_u64 v[38:39], v[36:37], 0, v[12:13]
	global_store_dwordx4 v[38:39], v[16:19], off nt
	v_or_b32_e32 v12, v40, v15
	v_lshlrev_b32_e32 v12, 11, v12
	v_cvt_pk_bf16_f32 v16, v23, v21
	v_cvt_pk_bf16_f32 v17, v25, v27
	v_cvt_pk_bf16_f32 v18, v29, v31
	v_cvt_pk_bf16_f32 v19, v33, v35
	ds_read2_b32 v[22:23], v11 offset0:49 offset1:57
	ds_read2_b32 v[24:25], v11 offset0:16 offset1:24
	ds_read2_b32 v[26:27], v11 offset0:82 offset1:90
	ds_read2_b32 v[28:29], v11 offset0:115 offset1:123
	ds_read2_b32 v[30:31], v11 offset0:148 offset1:156
	ds_read2_b32 v[32:33], v11 offset0:181 offset1:189
	ds_read2_b32 v[34:35], v11 offset0:214 offset1:222
	ds_read2_b32 v[38:39], v11 offset0:247 offset1:255
	v_lshl_add_u64 v[20:21], v[36:37], 0, v[12:13]
	v_or_b32_e32 v12, v40, v56
	v_lshlrev_b32_e32 v12, 11, v12
	global_store_dwordx4 v[20:21], v[16:19], off nt
	v_lshl_add_u64 v[20:21], v[36:37], 0, v[12:13]
	v_or_b32_e32 v12, v40, v57
	s_waitcnt lgkmcnt(6)
	v_cvt_pk_bf16_f32 v16, v24, v22
	s_waitcnt lgkmcnt(4)
	v_cvt_pk_bf16_f32 v17, v26, v28
	s_waitcnt lgkmcnt(2)
	v_cvt_pk_bf16_f32 v18, v30, v32
	s_waitcnt lgkmcnt(0)
	v_cvt_pk_bf16_f32 v19, v34, v38
	v_lshlrev_b32_e32 v12, 11, v12
	global_store_dwordx4 v[20:21], v[16:19], off nt
	v_lshl_add_u64 v[20:21], v[36:37], 0, v[12:13]
	s_nop 0
	v_cvt_pk_bf16_f32 v16, v25, v23
	v_cvt_pk_bf16_f32 v17, v27, v29
	v_cvt_pk_bf16_f32 v18, v31, v33
	v_cvt_pk_bf16_f32 v19, v35, v39
	global_store_dwordx4 v[20:21], v[16:19], off nt
	s_waitcnt lgkmcnt(0)

; #define LAS __attribute__((address_space(3)))
; __device__ __forceinline__ unsigned pk2(float lo, float hi) { return pg8::cvt_pk_bf16(lo, hi); }
; __device__ __forceinline__ void transpose_item(const float* W, int ldw, const float* kgain, float scale, bf16_t* WT, int ldt, int k0, int n_src0, int n_dst0, LAS float* scr, int lane) {
;     ...
;     for (int i = 0; i < 32; ++i) scr[(2 * i + (lane >> 5)) * 33 + (lane & 31)] = wv[i];
;     asm volatile("s_waitcnt lgkmcnt(0)" ::: "memory");
;     const int c = lane & 7;
; #pragma unroll
;     for (int j = 0; j < 4; ++j) { const int n = (lane >> 3) + 8 * j; const LAS float* s = scr + (8 * c) * 33 + n;
;         u32x4 o; o.x = pk2(s[0 * 33], s[1 * 33]); o.y = pk2(s[2 * 33], s[3 * 33]); o.z = pk2(s[4 * 33], s[5 * 33]); o.w = pk2(s[6 * 33], s[7 * 33]);
;         *(u32x4*)(WT + (size_t)(n_dst0 + n) * ldt + k0 + 8 * c) = o; }
;     asm volatile("s_waitcnt lgkmcnt(0)" ::: "memory");
.LBB0_44:
	v_add_u32_e32 v12, 0x400, v5
	s_waitcnt vmcnt(30)
	ds_write2_b32 v5, v20, v21 offset1:66
	s_waitcnt vmcnt(28)
	ds_write2_b32 v5, v22, v23 offset0:132 offset1:198
	s_waitcnt vmcnt(26)
	ds_write2_b32 v12, v24, v25 offset0:8 offset1:74
	s_waitcnt vmcnt(24)
	ds_write2_b32 v12, v26, v27 offset0:140 offset1:206
	v_add_u32_e32 v12, 0x800, v5
	s_waitcnt vmcnt(22)
	ds_write2_b32 v12, v28, v29 offset0:16 offset1:82
	s_waitcnt vmcnt(20)
	ds_write2_b32 v12, v30, v31 offset0:148 offset1:214
	v_add_u32_e32 v12, 0xc00, v5
	s_waitcnt vmcnt(18)
	ds_write2_b32 v12, v32, v33 offset0:24 offset1:90
	s_waitcnt vmcnt(16)
	ds_write2_b32 v12, v34, v35 offset0:156 offset1:222
	v_add_u32_e32 v12, 0x1000, v5
	s_waitcnt vmcnt(14)
	ds_write2_b32 v12, v36, v37 offset0:32 offset1:98
	s_waitcnt vmcnt(12)
	ds_write2_b32 v12, v38, v39 offset0:164 offset1:230
	v_add_u32_e32 v12, 0x1400, v5
	s_waitcnt vmcnt(10)
	ds_write2_b32 v12, v40, v41 offset0:40 offset1:106
	s_waitcnt vmcnt(8)
	ds_write2_b32 v12, v42, v43 offset0:172 offset1:238
	v_add_u32_e32 v12, 0x1800, v5
	s_waitcnt vmcnt(6)
	ds_write2_b32 v12, v44, v45 offset0:48 offset1:114
	s_waitcnt vmcnt(4)
	ds_write2_b32 v12, v46, v47 offset0:180 offset1:246
	v_add_u32_e32 v12, 0x1c00, v5
	s_waitcnt vmcnt(2)
	ds_write2_b32 v12, v48, v49 offset0:56 offset1:122
	s_waitcnt vmcnt(0)
	ds_write2_b32 v12, v50, v51 offset0:188 offset1:254
	s_waitcnt lgkmcnt(0)
	ds_read2_b32 v[20:21], v11 offset0:33 offset1:41
	ds_read2_b32 v[22:23], v11 offset1:8
	ds_read2_b32 v[24:25], v11 offset0:66 offset1:74
	ds_read2_b32 v[26:27], v11 offset0:99 offset1:107
	ds_read2_b32 v[28:29], v11 offset0:132 offset1:140
	ds_read2_b32 v[30:31], v11 offset0:165 offset1:173
	ds_read2_b32 v[32:33], v11 offset0:198 offset1:206
	ds_read2_b32 v[34:35], v11 offset0:231 offset1:239
	v_ashrrev_i32_e32 v19, 31, v18
	v_or_b32_e32 v38, v69, v7
	v_lshl_add_u64 v[16:17], v[18:19], 1, v[16:17]
	v_lshlrev_b32_e32 v12, 1, v14
	v_ashrrev_i32_e32 v39, 31, v38
	v_lshl_add_u64 v[36:37], v[16:17], 0, v[12:13]
	v_lshlrev_b64 v[38:39], 12, v[38:39]
	s_waitcnt lgkmcnt(6)
	v_cvt_pk_bf16_f32 v16, v22, v20
	s_waitcnt lgkmcnt(4)
	v_cvt_pk_bf16_f32 v17, v24, v26
	s_waitcnt lgkmcnt(2)
	v_cvt_pk_bf16_f32 v18, v28, v30
	s_waitcnt lgkmcnt(0)
	v_cvt_pk_bf16_f32 v19, v32, v34
	v_lshl_add_u64 v[38:39], v[36:37], 0, v[38:39]
	v_or_b32_e32 v20, v69, v15
	global_store_dwordx4 v[38:39], v[16:19], off nt
	s_nop 1
	v_cvt_pk_bf16_f32 v16, v23, v21
	v_ashrrev_i32_e32 v21, 31, v20
	v_cvt_pk_bf16_f32 v17, v25, v27
	v_cvt_pk_bf16_f32 v18, v29, v31
	v_cvt_pk_bf16_f32 v19, v33, v35
	v_lshlrev_b64 v[20:21], 12, v[20:21]
	ds_read2_b32 v[22:23], v11 offset0:49 offset1:57
	ds_read2_b32 v[24:25], v11 offset0:16 offset1:24
	ds_read2_b32 v[26:27], v11 offset0:82 offset1:90
	ds_read2_b32 v[28:29], v11 offset0:115 offset1:123
	ds_read2_b32 v[30:31], v11 offset0:148 offset1:156
	ds_read2_b32 v[32:33], v11 offset0:181 offset1:189
	ds_read2_b32 v[34:35], v11 offset0:214 offset1:222
	ds_read2_b32 v[38:39], v11 offset0:247 offset1:255
	v_lshl_add_u64 v[20:21], v[36:37], 0, v[20:21]
	global_store_dwordx4 v[20:21], v[16:19], off nt
	v_or_b32_e32 v20, v69, v56
	v_ashrrev_i32_e32 v21, 31, v20
	v_lshlrev_b64 v[20:21], 12, v[20:21]
	s_waitcnt lgkmcnt(6)
	v_cvt_pk_bf16_f32 v16, v24, v22
	s_waitcnt lgkmcnt(4)
	v_cvt_pk_bf16_f32 v17, v26, v28
	s_waitcnt lgkmcnt(2)
	v_cvt_pk_bf16_f32 v18, v30, v32
	s_waitcnt lgkmcnt(0)
	v_cvt_pk_bf16_f32 v19, v34, v38
	v_lshl_add_u64 v[20:21], v[36:37], 0, v[20:21]
	global_store_dwordx4 v[20:21], v[16:19], off nt
	v_or_b32_e32 v20, v69, v57
	v_ashrrev_i32_e32 v21, 31, v20
	v_lshlrev_b64 v[20:21], 12, v[20:21]
	v_cvt_pk_bf16_f32 v16, v25, v23
	v_cvt_pk_bf16_f32 v17, v27, v29
	v_cvt_pk_bf16_f32 v18, v31, v33
	v_cvt_pk_bf16_f32 v19, v35, v39
	v_lshl_add_u64 v[20:21], v[36:37], 0, v[20:21]
	global_store_dwordx4 v[20:21], v[16:19], off nt
	s_waitcnt lgkmcnt(0)

; __device__ __forceinline__ void fold_item(const float* Win, const float* wgg, const float* kgain, bf16_t* WT, int k0, int j0, int n_dst0, LAS float* scr, int lane) {
;     ...
;     for (int i = 0; i < 32; ++i) { const int kk = 2 * i + (lane >> 5); const f32x4* wr = (const f32x4*)(Win + (size_t)(k0 + kk) * NIN + C_GLR); float s = 0.f;
; #pragma unroll
;         for (int r4 = 0; r4 < GR / 4; ++r4) { const f32x4 x = wr[r4]; s += (x[0] * wg[4 * r4] + x[1] * wg[4 * r4 + 1]) + (x[2] * wg[4 * r4 + 2] + x[3] * wg[4 * r4 + 3]); }
;         scr[kk * 33 + (lane & 31)] = s * kgain[k0 + kk]; }
.LBB0_47:
	v_lshl_add_u64 v[54:55], v[52:53], 0, s[84:85]
	v_lshl_add_u64 v[86:87], v[54:55], 0, s[78:79]
	v_add_co_u32_e32 v54, vcc, 0x7000, v54
	s_nop 1
	v_addc_co_u32_e32 v55, vcc, 0, v55, vcc
	global_load_dwordx4 v[74:77], v[54:55], off
	global_load_dwordx4 v[78:81], v[86:87], off offset:32
	global_load_dwordx4 v[82:85], v[86:87], off offset:48
	s_nop 0
	global_load_dwordx4 v[86:89], v[86:87], off offset:16
	s_waitcnt vmcnt(3)
	v_mov_b32_e32 v54, v75
	v_mov_b32_e32 v75, v77
	v_mov_b32_e32 v55, v76
	v_pk_mul_f32 v[74:75], v[20:21], v[74:75]
	s_nop 0
	v_pk_fma_f32 v[54:55], v[22:23], v[54:55], v[74:75]
	s_waitcnt vmcnt(0)
	v_mov_b32_e32 v74, v87
	v_mov_b32_e32 v87, v89
	v_mov_b32_e32 v75, v88
	v_pk_mul_f32 v[76:77], v[24:25], v[86:87]
	v_add_f32_e32 v54, v54, v55
	v_pk_fma_f32 v[74:75], v[26:27], v[74:75], v[76:77]
	v_mul_f32_e32 v76, v70, v83
	v_pk_add_f32 v[74:75], v[74:75], v[74:75] op_sel:[0,1] op_sel_hi:[1,0]
	v_add_f32_e32 v54, 0, v54
	v_mul_f32_e32 v55, v12, v82
	v_mov_b32_e32 v75, v76
	v_pk_add_f32 v[54:55], v[54:55], v[74:75]
	v_mul_f32_e32 v74, v29, v79
	v_mul_f32_e32 v77, v71, v84
	v_pk_fma_f32 v[74:75], v[28:29], v[78:79], v[74:75] op_sel_hi:[1,1,0]
	v_mul_f32_e32 v76, v31, v81
	v_mul_f32_e32 v82, v72, v85
	v_mov_b32_e32 v75, v77
	v_pk_fma_f32 v[76:77], v[30:31], v[80:81], v[76:77] op_sel_hi:[1,1,0]
	s_nop 0
	v_mov_b32_e32 v77, v82
	v_pk_add_f32 v[74:75], v[74:75], v[76:77]
	s_nop 0
	v_pk_add_f32 v[54:55], v[54:55], v[74:75]
	s_nop 0
	v_add_f32_e32 v74, v54, v55
	v_lshl_add_u64 v[54:55], v[50:51], 0, v[46:47]
	global_load_dword v54, v[54:55], off
	v_lshl_add_u64 v[50:51], v[50:51], 0, 64
	s_waitcnt vmcnt(0)
	v_mul_f32_e32 v90, v54, v74
	v_lshl_add_u64 v[54:55], v[44:45], 0, s[84:85]
	v_lshl_add_u64 v[86:87], v[54:55], 0, s[78:79]
	v_add_co_u32_e32 v54, vcc, s25, v54
	s_nop 1
	v_addc_co_u32_e32 v55, vcc, 0, v55, vcc
	global_load_dwordx4 v[74:77], v[54:55], off
	global_load_dwordx4 v[78:81], v[86:87], off offset:32
	global_load_dwordx4 v[82:85], v[86:87], off offset:48
	s_nop 0
	global_load_dwordx4 v[86:89], v[86:87], off offset:16
	s_waitcnt vmcnt(3)
	v_mov_b32_e32 v54, v75
	v_mov_b32_e32 v75, v77
	v_mov_b32_e32 v55, v76
	v_pk_mul_f32 v[74:75], v[20:21], v[74:75]
	s_nop 0
	v_pk_fma_f32 v[54:55], v[22:23], v[54:55], v[74:75]
	s_waitcnt vmcnt(0)
	v_mov_b32_e32 v74, v87
	v_mov_b32_e32 v87, v89
	v_mov_b32_e32 v75, v88
	v_pk_mul_f32 v[76:77], v[24:25], v[86:87]
	v_add_f32_e32 v54, v54, v55
	v_pk_fma_f32 v[74:75], v[26:27], v[74:75], v[76:77]
	v_mul_f32_e32 v76, v70, v83
	v_pk_add_f32 v[74:75], v[74:75], v[74:75] op_sel:[0,1] op_sel_hi:[1,0]
	v_add_f32_e32 v54, 0, v54
	v_mul_f32_e32 v55, v12, v82
	v_mov_b32_e32 v75, v76
	v_pk_add_f32 v[54:55], v[54:55], v[74:75]
	v_mul_f32_e32 v74, v29, v79
	v_mul_f32_e32 v77, v71, v84
	v_pk_fma_f32 v[74:75], v[28:29], v[78:79], v[74:75] op_sel_hi:[1,1,0]
	v_mul_f32_e32 v76, v31, v81
	v_mul_f32_e32 v82, v72, v85
	v_mov_b32_e32 v75, v77
	v_pk_fma_f32 v[76:77], v[30:31], v[80:81], v[76:77] op_sel_hi:[1,1,0]
	s_nop 0
	v_mov_b32_e32 v77, v82
	v_pk_add_f32 v[74:75], v[74:75], v[76:77]
	s_nop 0
	v_pk_add_f32 v[54:55], v[54:55], v[74:75]
	s_nop 0
	v_add_f32_e32 v74, v54, v55
	v_lshl_add_u64 v[54:55], v[48:49], 0, v[46:47]
	global_load_dword v75, v[54:55], off offset:8
	v_lshl_add_u64 v[48:49], v[48:49], 0, 64
	s_waitcnt vmcnt(0)
	v_mul_f32_e32 v74, v75, v74
	ds_write2_b32 v73, v90, v74 offset1:66
	v_lshl_add_u64 v[74:75], v[42:43], 0, s[84:85]
	v_lshl_add_u64 v[86:87], v[74:75], 0, s[78:79]
	v_add_co_u32_e32 v74, vcc, s25, v74
	s_nop 1
	v_addc_co_u32_e32 v75, vcc, 0, v75, vcc
	global_load_dwordx4 v[74:77], v[74:75], off
	s_nop 0
	global_load_dwordx4 v[78:81], v[86:87], off offset:32
	global_load_dwordx4 v[82:85], v[86:87], off offset:48
	s_nop 0
	global_load_dwordx4 v[86:89], v[86:87], off offset:16
	s_waitcnt vmcnt(3)
	v_mov_b32_e32 v90, v75
	v_mov_b32_e32 v91, v76
	v_mov_b32_e32 v75, v77
	s_waitcnt vmcnt(0)
	v_mov_b32_e32 v76, v87
	v_mov_b32_e32 v87, v89
	v_pk_mul_f32 v[74:75], v[20:21], v[74:75]
	v_mov_b32_e32 v77, v88
	v_pk_mul_f32 v[86:87], v[24:25], v[86:87]
	v_pk_fma_f32 v[74:75], v[22:23], v[90:91], v[74:75]
	v_pk_fma_f32 v[76:77], v[26:27], v[76:77], v[86:87]
	v_add_f32_e32 v74, v74, v75
	v_mul_f32_e32 v75, v12, v82
	v_mul_f32_e32 v82, v70, v83
	v_pk_add_f32 v[76:77], v[76:77], v[76:77] op_sel:[0,1] op_sel_hi:[1,0]
	v_add_f32_e32 v74, 0, v74
	v_mov_b32_e32 v77, v82
	v_pk_add_f32 v[74:75], v[74:75], v[76:77]
	v_mul_f32_e32 v76, v29, v79
	v_pk_fma_f32 v[76:77], v[28:29], v[78:79], v[76:77] op_sel_hi:[1,1,0]
	v_mul_f32_e32 v78, v31, v81
	v_mul_f32_e32 v83, v71, v84
	v_mul_f32_e32 v84, v72, v85
	v_pk_fma_f32 v[78:79], v[30:31], v[80:81], v[78:79] op_sel_hi:[1,1,0]
	v_mov_b32_e32 v77, v83
	v_mov_b32_e32 v79, v84
	v_pk_add_f32 v[76:77], v[76:77], v[78:79]
	s_nop 0
	v_pk_add_f32 v[74:75], v[74:75], v[76:77]
	s_nop 0
	v_add_f32_e32 v74, v74, v75
	global_load_dword v75, v[54:55], off offset:16
	s_waitcnt vmcnt(0)
	v_mul_f32_e32 v92, v75, v74
	v_lshl_add_u64 v[74:75], v[40:41], 0, s[84:85]
	v_lshl_add_u64 v[86:87], v[74:75], 0, s[78:79]
	v_add_co_u32_e32 v74, vcc, s25, v74
	s_nop 1
	v_addc_co_u32_e32 v75, vcc, 0, v75, vcc
	global_load_dwordx4 v[74:77], v[74:75], off
	s_nop 0
	global_load_dwordx4 v[78:81], v[86:87], off offset:32
	global_load_dwordx4 v[82:85], v[86:87], off offset:48
	s_nop 0
	global_load_dwordx4 v[86:89], v[86:87], off offset:16
	s_waitcnt vmcnt(3)
	v_mov_b32_e32 v90, v75
	v_mov_b32_e32 v91, v76
	v_mov_b32_e32 v75, v77
	s_waitcnt vmcnt(0)
; #define LAS __attribute__((address_space(3)))
; __device__ __forceinline__ void fold_item(const float* Win, const float* wgg, const float* kgain, bf16_t* WT, int k0, int j0, int n_dst0, LAS float* scr, int lane) {
;     float wg[GR];
; #pragma unroll
;     for (int r = 0; r < GR; ++r) wg[r] = wgg[r * GKW + j0 + (lane & 31)];
; #pragma unroll 8
;     for (int i = 0; i < 32; ++i) { const int kk = 2 * i + (lane >> 5); const f32x4* wr = (const f32x4*)(Win + (size_t)(k0 + kk) * NIN + C_GLR); float s = 0.f;
; #pragma unroll
;         for (int r4 = 0; r4 < GR / 4; ++r4) { const f32x4 x = wr[r4]; s += (x[0] * wg[4 * r4] + x[1] * wg[4 * r4 + 1]) + (x[2] * wg[4 * r4 + 2] + x[3] * wg[4 * r4 + 3]); }
;         scr[kk * 33 + (lane & 31)] = s * kgain[k0 + kk]; }
	v_mov_b32_e32 v76, v87
	v_mov_b32_e32 v87, v89
	v_pk_mul_f32 v[74:75], v[20:21], v[74:75]
	v_mov_b32_e32 v77, v88
	v_pk_mul_f32 v[86:87], v[24:25], v[86:87]
	v_pk_fma_f32 v[74:75], v[22:23], v[90:91], v[74:75]
	v_pk_fma_f32 v[76:77], v[26:27], v[76:77], v[86:87]
	v_add_f32_e32 v74, v74, v75
	v_mul_f32_e32 v75, v12, v82
	v_mul_f32_e32 v82, v70, v83
	v_pk_add_f32 v[76:77], v[76:77], v[76:77] op_sel:[0,1] op_sel_hi:[1,0]
	v_add_f32_e32 v74, 0, v74
	v_mov_b32_e32 v77, v82
	v_pk_add_f32 v[74:75], v[74:75], v[76:77]
	v_mul_f32_e32 v76, v29, v79
	v_pk_fma_f32 v[76:77], v[28:29], v[78:79], v[76:77] op_sel_hi:[1,1,0]
	v_mul_f32_e32 v78, v31, v81
	v_mul_f32_e32 v83, v71, v84
	v_mul_f32_e32 v84, v72, v85
	v_pk_fma_f32 v[78:79], v[30:31], v[80:81], v[78:79] op_sel_hi:[1,1,0]
	v_mov_b32_e32 v77, v83
	v_mov_b32_e32 v79, v84
	v_pk_add_f32 v[76:77], v[76:77], v[78:79]
	s_nop 0
	v_pk_add_f32 v[74:75], v[74:75], v[76:77]
	s_nop 0
	v_add_f32_e32 v74, v74, v75
	global_load_dword v75, v[54:55], off offset:24
	s_waitcnt vmcnt(0)
	v_mul_f32_e32 v74, v75, v74
	ds_write2_b32 v73, v92, v74 offset0:132 offset1:198
	v_lshl_add_u64 v[74:75], v[38:39], 0, s[84:85]
	v_lshl_add_u64 v[86:87], v[74:75], 0, s[78:79]
	v_add_co_u32_e32 v74, vcc, s25, v74
	s_nop 1
	v_addc_co_u32_e32 v75, vcc, 0, v75, vcc
	global_load_dwordx4 v[74:77], v[74:75], off
	s_nop 0
	global_load_dwordx4 v[78:81], v[86:87], off offset:32
	global_load_dwordx4 v[82:85], v[86:87], off offset:48
	s_nop 0
	global_load_dwordx4 v[86:89], v[86:87], off offset:16
	s_waitcnt vmcnt(3)
	v_mov_b32_e32 v90, v75
	v_mov_b32_e32 v91, v76
	v_mov_b32_e32 v75, v77
	s_waitcnt vmcnt(0)
	v_mov_b32_e32 v76, v87
	v_mov_b32_e32 v87, v89
	v_pk_mul_f32 v[74:75], v[20:21], v[74:75]
	v_mov_b32_e32 v77, v88
	v_pk_mul_f32 v[86:87], v[24:25], v[86:87]
	v_pk_fma_f32 v[74:75], v[22:23], v[90:91], v[74:75]
	v_pk_fma_f32 v[76:77], v[26:27], v[76:77], v[86:87]
	v_add_f32_e32 v74, v74, v75
	v_mul_f32_e32 v75, v12, v82
	v_mul_f32_e32 v82, v70, v83
	v_pk_add_f32 v[76:77], v[76:77], v[76:77] op_sel:[0,1] op_sel_hi:[1,0]
	v_add_f32_e32 v74, 0, v74
	v_mov_b32_e32 v77, v82
	v_pk_add_f32 v[74:75], v[74:75], v[76:77]
	v_mul_f32_e32 v76, v29, v79
	v_pk_fma_f32 v[76:77], v[28:29], v[78:79], v[76:77] op_sel_hi:[1,1,0]
	v_mul_f32_e32 v78, v31, v81
	v_mul_f32_e32 v83, v71, v84
	v_mul_f32_e32 v84, v72, v85
	v_pk_fma_f32 v[78:79], v[30:31], v[80:81], v[78:79] op_sel_hi:[1,1,0]
	v_mov_b32_e32 v77, v83
	v_mov_b32_e32 v79, v84
	v_pk_add_f32 v[76:77], v[76:77], v[78:79]
	s_nop 0
	v_pk_add_f32 v[74:75], v[74:75], v[76:77]
	s_nop 0
	v_add_f32_e32 v74, v74, v75
	global_load_dword v75, v[54:55], off offset:32
	s_waitcnt vmcnt(0)
	v_mul_f32_e32 v92, v75, v74
	v_lshl_add_u64 v[74:75], v[36:37], 0, s[84:85]
	v_lshl_add_u64 v[86:87], v[74:75], 0, s[78:79]
	v_add_co_u32_e32 v74, vcc, s25, v74
	s_nop 1
	v_addc_co_u32_e32 v75, vcc, 0, v75, vcc
	global_load_dwordx4 v[74:77], v[74:75], off
	s_nop 0
	global_load_dwordx4 v[78:81], v[86:87], off offset:32
	global_load_dwordx4 v[82:85], v[86:87], off offset:48
	s_nop 0
	global_load_dwordx4 v[86:89], v[86:87], off offset:16
	s_waitcnt vmcnt(3)
	v_mov_b32_e32 v90, v75
	v_mov_b32_e32 v91, v76
	v_mov_b32_e32 v75, v77
	s_waitcnt vmcnt(0)
	v_mov_b32_e32 v76, v87
	v_mov_b32_e32 v87, v89
	v_pk_mul_f32 v[74:75], v[20:21], v[74:75]
	v_mov_b32_e32 v77, v88
	v_pk_mul_f32 v[86:87], v[24:25], v[86:87]
	v_pk_fma_f32 v[74:75], v[22:23], v[90:91], v[74:75]
	v_pk_fma_f32 v[76:77], v[26:27], v[76:77], v[86:87]
	v_add_f32_e32 v74, v74, v75
	v_mul_f32_e32 v75, v12, v82
	v_mul_f32_e32 v82, v70, v83
	v_pk_add_f32 v[76:77], v[76:77], v[76:77] op_sel:[0,1] op_sel_hi:[1,0]
	v_add_f32_e32 v74, 0, v74
	v_mov_b32_e32 v77, v82
	v_pk_add_f32 v[74:75], v[74:75], v[76:77]
	v_mul_f32_e32 v76, v29, v79
	v_pk_fma_f32 v[76:77], v[28:29], v[78:79], v[76:77] op_sel_hi:[1,1,0]
	v_mul_f32_e32 v78, v31, v81
	v_mul_f32_e32 v83, v71, v84
	v_mul_f32_e32 v84, v72, v85
	v_pk_fma_f32 v[78:79], v[30:31], v[80:81], v[78:79] op_sel_hi:[1,1,0]
	v_mov_b32_e32 v77, v83
	v_mov_b32_e32 v79, v84
	v_pk_add_f32 v[76:77], v[76:77], v[78:79]
	s_nop 0
	v_pk_add_f32 v[74:75], v[74:75], v[76:77]
	v_lshl_add_u64 v[76:77], v[34:35], 0, s[84:85]
	v_add_f32_e32 v74, v74, v75
	global_load_dword v75, v[54:55], off offset:40
	v_lshl_add_u64 v[88:89], v[76:77], 0, s[78:79]
	v_add_co_u32_e32 v76, vcc, s25, v76
	s_waitcnt vmcnt(0)
	v_mul_f32_e32 v75, v75, v74
	v_add_u32_e32 v74, 0x400, v73
	ds_write2_b32 v74, v92, v75 offset0:8 offset1:74
	v_addc_co_u32_e32 v77, vcc, 0, v77, vcc
	global_load_dwordx4 v[76:79], v[76:77], off
	s_nop 0
	global_load_dwordx4 v[80:83], v[88:89], off offset:32
	global_load_dwordx4 v[84:87], v[88:89], off offset:48
	s_nop 0
	global_load_dwordx4 v[88:91], v[88:89], off offset:16
	v_add_u32_e32 v73, 0x840, v73
	s_waitcnt vmcnt(3)
	v_mov_b32_e32 v92, v77
	v_mov_b32_e32 v77, v79
	v_mov_b32_e32 v93, v78
	v_pk_mul_f32 v[76:77], v[20:21], v[76:77]
	s_waitcnt vmcnt(0)
; #define LAS __attribute__((address_space(3)))
; __device__ __forceinline__ unsigned pk2(float lo, float hi) { return pg8::cvt_pk_bf16(lo, hi); }
; __device__ __forceinline__ void fold_item(const float* Win, const float* wgg, const float* kgain, bf16_t* WT, int k0, int j0, int n_dst0, LAS float* scr, int lane) {
;     ...
;     for (int i = 0; i < 32; ++i) { const int kk = 2 * i + (lane >> 5); const f32x4* wr = (const f32x4*)(Win + (size_t)(k0 + kk) * NIN + C_GLR); float s = 0.f;
; #pragma unroll
;         for (int r4 = 0; r4 < GR / 4; ++r4) { const f32x4 x = wr[r4]; s += (x[0] * wg[4 * r4] + x[1] * wg[4 * r4 + 1]) + (x[2] * wg[4 * r4 + 2] + x[3] * wg[4 * r4 + 3]); }
;         scr[kk * 33 + (lane & 31)] = s * kgain[k0 + kk]; }
;     asm volatile("s_waitcnt lgkmcnt(0)" ::: "memory");
;     const int c = lane & 7;
; #pragma unroll
;     for (int j = 0; j < 4; ++j) { const int n = (lane >> 3) + 8 * j; const LAS float* s = scr + (8 * c) * 33 + n;
;         u32x4 o; o.x = pk2(s[0 * 33], s[1 * 33]); o.y = pk2(s[2 * 33], s[3 * 33]); o.z = pk2(s[4 * 33], s[5 * 33]); o.w = pk2(s[6 * 33], s[7 * 33]);
;         *(u32x4*)(WT + (size_t)(n_dst0 + n) * D + k0 + 8 * c) = o; }
;     asm volatile("s_waitcnt lgkmcnt(0)" ::: "memory");
	v_mov_b32_e32 v78, v89
	v_mov_b32_e32 v89, v91
	v_pk_fma_f32 v[76:77], v[22:23], v[92:93], v[76:77]
	v_mov_b32_e32 v79, v90
	v_pk_mul_f32 v[88:89], v[24:25], v[88:89]
	v_add_f32_e32 v75, v76, v77
	v_pk_fma_f32 v[78:79], v[26:27], v[78:79], v[88:89]
	v_add_f32_e32 v76, 0, v75
	v_mul_f32_e32 v75, v70, v85
	v_pk_add_f32 v[78:79], v[78:79], v[78:79] op_sel:[0,1] op_sel_hi:[1,0]
	v_mul_f32_e32 v77, v12, v84
	v_mov_b32_e32 v79, v75
	v_pk_add_f32 v[76:77], v[76:77], v[78:79]
	v_mul_f32_e32 v78, v29, v81
	v_pk_fma_f32 v[78:79], v[28:29], v[80:81], v[78:79] op_sel_hi:[1,1,0]
	v_mul_f32_e32 v80, v31, v83
	v_mul_f32_e32 v84, v71, v86
	v_mul_f32_e32 v85, v72, v87
	v_pk_fma_f32 v[80:81], v[30:31], v[82:83], v[80:81] op_sel_hi:[1,1,0]
	v_mov_b32_e32 v79, v84
	v_mov_b32_e32 v81, v85
	v_pk_add_f32 v[78:79], v[78:79], v[80:81]
	s_nop 0
	v_pk_add_f32 v[76:77], v[76:77], v[78:79]
	s_nop 0
	v_add_f32_e32 v75, v76, v77
	global_load_dword v76, v[54:55], off offset:48
	s_waitcnt vmcnt(0)
	v_mul_f32_e32 v75, v76, v75
	v_lshl_add_u64 v[76:77], v[32:33], 0, s[84:85]
	v_lshl_add_u64 v[88:89], v[76:77], 0, s[78:79]
	v_add_co_u32_e32 v76, vcc, s25, v76
	s_add_u32 s84, s84, 0xb0400
	s_nop 0
	v_addc_co_u32_e32 v77, vcc, 0, v77, vcc
	global_load_dwordx4 v[76:79], v[76:77], off
	s_nop 0
	global_load_dwordx4 v[80:83], v[88:89], off offset:32
	global_load_dwordx4 v[84:87], v[88:89], off offset:48
	s_nop 0
	global_load_dwordx4 v[88:91], v[88:89], off offset:16
	s_addc_u32 s85, s85, 0
	global_load_dword v54, v[54:55], off offset:56
	s_cmp_lg_u32 s84, 0x2c1000
	s_waitcnt vmcnt(4)
	v_mov_b32_e32 v92, v77
	v_mov_b32_e32 v93, v78
	v_mov_b32_e32 v77, v79
	s_waitcnt vmcnt(1)
	v_mov_b32_e32 v78, v89
	v_mov_b32_e32 v89, v91
	v_pk_mul_f32 v[76:77], v[20:21], v[76:77]
	v_mov_b32_e32 v79, v90
	v_pk_mul_f32 v[88:89], v[24:25], v[88:89]
	v_pk_fma_f32 v[76:77], v[22:23], v[92:93], v[76:77]
	v_pk_fma_f32 v[78:79], v[26:27], v[78:79], v[88:89]
	v_add_f32_e32 v76, v76, v77
	v_mul_f32_e32 v77, v12, v84
	v_mul_f32_e32 v84, v70, v85
	v_pk_add_f32 v[78:79], v[78:79], v[78:79] op_sel:[0,1] op_sel_hi:[1,0]
	v_add_f32_e32 v76, 0, v76
	v_mov_b32_e32 v79, v84
	v_pk_add_f32 v[76:77], v[76:77], v[78:79]
	v_mul_f32_e32 v78, v29, v81
	v_pk_fma_f32 v[78:79], v[28:29], v[80:81], v[78:79] op_sel_hi:[1,1,0]
	v_mul_f32_e32 v80, v31, v83
	v_mul_f32_e32 v85, v71, v86
	v_mul_f32_e32 v86, v72, v87
	v_pk_fma_f32 v[80:81], v[30:31], v[82:83], v[80:81] op_sel_hi:[1,1,0]
	v_mov_b32_e32 v79, v85
	v_mov_b32_e32 v81, v86
	v_pk_add_f32 v[78:79], v[78:79], v[80:81]
	s_nop 0
	v_pk_add_f32 v[76:77], v[76:77], v[78:79]
	s_nop 0
	v_add_f32_e32 v76, v76, v77
	s_waitcnt vmcnt(0)
	v_mul_f32_e32 v54, v54, v76
	ds_write2_b32 v74, v75, v54 offset0:140 offset1:206
	s_cbranch_scc1 .LBB0_47
	s_waitcnt lgkmcnt(0)
	ds_read2_b32 v[20:21], v11 offset0:33 offset1:41
	ds_read2_b32 v[22:23], v11 offset1:8
	ds_read2_b32 v[24:25], v11 offset0:66 offset1:74
	ds_read2_b32 v[26:27], v11 offset0:99 offset1:107
	ds_read2_b32 v[28:29], v11 offset0:132 offset1:140
	ds_read2_b32 v[30:31], v11 offset0:165 offset1:173
	ds_read2_b32 v[32:33], v11 offset0:198 offset1:206
	ds_read2_b32 v[34:35], v11 offset0:231 offset1:239
	v_lshl_add_u64 v[16:17], v[18:19], 1, v[16:17]
	v_lshlrev_b32_e32 v12, 1, v14
	v_lshl_add_u64 v[36:37], v[16:17], 0, v[12:13]
	v_or_b32_e32 v12, v69, v7
	v_lshlrev_b32_e32 v12, 12, v12
	s_waitcnt lgkmcnt(6)
	v_cvt_pk_bf16_f32 v16, v22, v20
	s_waitcnt lgkmcnt(4)
	v_cvt_pk_bf16_f32 v17, v24, v26
	s_waitcnt lgkmcnt(2)
	v_cvt_pk_bf16_f32 v18, v28, v30
	s_waitcnt lgkmcnt(0)
	v_cvt_pk_bf16_f32 v19, v32, v34
	v_lshl_add_u64 v[38:39], v[36:37], 0, v[12:13]
	global_store_dwordx4 v[38:39], v[16:19], off nt
	v_or_b32_e32 v12, v69, v15
	v_lshlrev_b32_e32 v12, 12, v12
	v_cvt_pk_bf16_f32 v16, v23, v21
	v_cvt_pk_bf16_f32 v17, v25, v27
	v_cvt_pk_bf16_f32 v18, v29, v31
	v_cvt_pk_bf16_f32 v19, v33, v35
	ds_read2_b32 v[22:23], v11 offset0:49 offset1:57
	ds_read2_b32 v[24:25], v11 offset0:16 offset1:24
	ds_read2_b32 v[26:27], v11 offset0:82 offset1:90
	ds_read2_b32 v[28:29], v11 offset0:115 offset1:123
	ds_read2_b32 v[30:31], v11 offset0:148 offset1:156
	ds_read2_b32 v[32:33], v11 offset0:181 offset1:189
	ds_read2_b32 v[34:35], v11 offset0:214 offset1:222
	ds_read2_b32 v[38:39], v11 offset0:247 offset1:255
	v_lshl_add_u64 v[20:21], v[36:37], 0, v[12:13]
	v_or_b32_e32 v12, v69, v56
	v_lshlrev_b32_e32 v12, 12, v12
	global_store_dwordx4 v[20:21], v[16:19], off nt
	v_lshl_add_u64 v[20:21], v[36:37], 0, v[12:13]
	v_or_b32_e32 v12, v69, v57
	s_waitcnt lgkmcnt(6)
	v_cvt_pk_bf16_f32 v16, v24, v22
	s_waitcnt lgkmcnt(4)
	v_cvt_pk_bf16_f32 v17, v26, v28
	s_waitcnt lgkmcnt(2)
	v_cvt_pk_bf16_f32 v18, v30, v32
	s_waitcnt lgkmcnt(0)
	v_cvt_pk_bf16_f32 v19, v34, v38
	v_lshlrev_b32_e32 v12, 12, v12
	global_store_dwordx4 v[20:21], v[16:19], off nt
	v_lshl_add_u64 v[20:21], v[36:37], 0, v[12:13]
	s_nop 0
	v_cvt_pk_bf16_f32 v16, v25, v23
	v_cvt_pk_bf16_f32 v17, v27, v29
	v_cvt_pk_bf16_f32 v18, v31, v33
	v_cvt_pk_bf16_f32 v19, v35, v39
	global_store_dwordx4 v[20:21], v[16:19], off nt
	s_waitcnt lgkmcnt(0)
	s_branch .LBB0_10
